# LRU pass 2: gelu-branch tile prefetched by LDS-DMA one tile ahead (double-buffered), read with ds_read_u16
# baseline (speedup 1.0000x reference)
; __device__ __forceinline__ float bf2f(u16 h) { return __uint_as_float(((unsigned)h) << 16); }
; __device__ __forceinline__ void lru_tile(const Params& P, int chunk, int head, int pass, char* smem_raw) {
;     ...
;   const int tid = VTID, lane = tid & 63, wid = tid >> 6;
;   const int q = tid >> 6, ch = tid & 63;
;   const int row0 = chunk * 128;
;   int seq_lo, seq_hi;
;   if (chunk < 256) { seq_lo = (chunk >> 6) << 13; seq_hi = seq_lo + 8192; }
;   else { const int b = (chunk - 256) >> 1; seq_lo = N_X + b * 256; seq_hi = seq_lo + 256; }
;   const int gch = head * 64 + ch;
;   const float* hfbuf = reinterpret_cast<const float*>(P.hy);
;   float* hfw = reinterpret_cast<float*>(P.hy);
;   {
;     const float w0 = P.conv_w[gch], w1 = P.conv_w[512 + gch], w2 = P.conv_w[1024 + gch], w3 = P.conv_w[1536 + gch];
;     const float cb = P.conv_b[gch];
;     const u16* zu = P.zq + gch;
;     const int r = row0 + q * 32;
;     float uv[35];
; #pragma unroll
;     for (int i = 0; i < 35; ++i) {
;       const int rr = r - 2 + i;
;       uv[i] = (rr >= seq_lo && rr < seq_hi) ? bf2f(zu[(long)rr * 1536]) : 0.f;
; __device__ __forceinline__ void run_phase(const Params& P, const int ph, char* smem_raw) {
;     ...
;       for (int t = VBID; t < 2112; t += VGRID) lru_tile(P, t >> 3, t & 7, 2, smv_raw);
.LBB0_477:
	v_readlane_b32 s0, v252, 0
	v_readlane_b32 s1, v252, 1
	v_readfirstlane_b32 s68, v153
	s_nop 3
	s_sub_u32 s0, s0, 0x170
	s_subb_u32 s1, s1, 0
	s_load_dwordx2 s[10:11], s[0:1], 0x148
	s_load_dwordx2 s[12:13], s[0:1], 0x158
	s_load_dwordx2 s[18:19], s[0:1], 0x130
	s_load_dwordx2 s[20:21], s[0:1], 0x128
	s_load_dwordx4 s[24:27], s[0:1], 0x70
	s_load_dwordx2 s[28:29], s[0:1], 0x88
	s_load_dwordx2 s[30:31], s[0:1], 0x98
	s_load_dwordx2 s[36:37], s[0:1], 0xa0
	s_lshl_b32 s4, s2, 1
	s_add_u32 s68, s4, s68
	s_mov_b32 s69, 0
	s_mov_b32 s70, 4
	s_cmp_lt_u32 s68, 64
	s_cselect_b32 s70, 5, 4
	s_mov_b32 s72, 0xffff0000
	s_mov_b32 s73, -1
	s_mov_b32 s74, 0
	s_mov_b32 s75, -1
	s_mov_b32 s76, 0
	s_mov_b32 s77, 0xffff0000
	s_mov_b32 s78, -1
	s_mov_b32 s79, 0x0000ffff
	s_mov_b32 s80, -1
	s_mov_b32 s81, 0
	s_mov_b32 s82, 0x0000ffff
	s_mov_b32 s83, 0
	v_and_b32_e32 v138, 63, v152
	v_lshrrev_b32_e32 v139, 4, v138
	v_and_b32_e32 v140, 15, v138
	v_bfe_u32 v141, v152, 6, 2
	v_lshl_add_u32 v255, v141, 4, v140
	v_mul_u32_u24_e32 v253, 0x12000, v153
	v_add_u32_e32 v253, 16, v253
	v_mul_u32_u24_e32 v134, 0x18000, v139
	v_lshl_add_u32 v134, v255, 1, v134
	v_lshlrev_b32_e32 v237, 16, v139
	v_lshl_add_u32 v237, v255, 1, v237
	v_lshlrev_b32_e32 v250, 3, v255
	v_lshlrev_b32_e32 v251, 7, v255
	v_lshl_add_u32 v251, v139, 4, v251
	v_lshrrev_b32_e32 v254, 3, v140
	v_lshl_add_u32 v254, v141, 1, v254
	v_lshlrev_b32_e32 v202, 1, v139
	v_xor_b32_e32 v89, v254, v202
	v_xor_b32_e32 v130, 1, v89
	v_and_b32_e32 v203, 7, v140
	v_lshl_add_u32 v202, v139, 12, v253
	v_lshl_add_u32 v202, v203, 1, v202
	v_lshl_add_u32 v89, v89, 4, v202
	v_lshl_add_u32 v130, v130, 4, v202
	v_lshrrev_b32_e32 v202, 2, v140
	v_and_b32_e32 v203, 3, v140
	v_lshl_add_u32 v254, v202, 5, v203
	v_lshl_add_u32 v254, v254, 7, v253
	v_lshrrev_b32_e32 v203, 1, v203
	v_lshl_add_u32 v202, v202, 1, v203
	v_xor_b32_e32 v202, v139, v202
	v_lshl_add_u32 v131, v202, 4, v254
	v_xor_b32_e32 v202, 4, v202
	v_lshl_add_u32 v133, v202, 4, v254
	v_cmp_eq_u32_e32 vcc, 0, v139
	s_mov_b64 s[84:85], vcc
	v_cmp_eq_u32_e32 vcc, 3, v139
	s_mov_b64 s[86:87], vcc
	s_waitcnt lgkmcnt(0)
	s_and_b32 s56, s68, 7
	s_lshl_b32 s56, s56, 6
	s_lshr_b32 s59, s68, 3
	s_cmp_lt_u32 s59, 256
	s_cselect_b32 s60, 63, 1
	s_and_b32 s57, s59, s60
	s_cmp_eq_u32 s57, 0
	s_cselect_b64 s[0:1], s[84:85], 0
	s_cmp_eq_u32 s57, s60
	s_cselect_b64 s[4:5], s[86:87], 0
	v_mov_b32_e32 v255, 0x1800
	v_cndmask_b32_e64 v150, 0, v255, s[0:1]
	v_lshlrev_b32_e32 v136, 1, v150
	v_add_u32_e32 v136, v134, v136
	v_add_u32_e32 v150, v134, v150
	v_cndmask_b32_e64 v151, 0, v255, s[4:5]
	v_sub_u32_e32 v151, v134, v151
	s_lshl_b32 s61, s59, 7
	s_mul_i32 s0, s61, 0xc00
	s_lshl_b32 s1, s56, 1
	s_add_u32 s0, s0, s1
	s_add_u32 s4, s10, s0
	s_addc_u32 s5, s11, 0
	s_sub_u32 s4, s4, 0x1800
	s_subb_u32 s5, s5, 0
	global_load_ushort v32, v136, s[4:5]
	s_add_u32 s4, s4, 0xc00
	s_addc_u32 s5, s5, 0
	global_load_ushort v33, v150, s[4:5]
	s_add_u32 s4, s4, 0xc00
	s_addc_u32 s5, s5, 0
	global_load_ushort v34, v134, s[4:5]
	s_add_u32 s4, s4, 0xc00
	s_addc_u32 s5, s5, 0
	global_load_ushort v35, v134, s[4:5]
	s_add_u32 s4, s4, 0xc00
	s_addc_u32 s5, s5, 0
	global_load_ushort v36, v134, s[4:5]
	s_add_u32 s4, s4, 0xc00
	s_addc_u32 s5, s5, 0
	global_load_ushort v37, v134, s[4:5]
	s_add_u32 s4, s4, 0xc00
	s_addc_u32 s5, s5, 0
	global_load_ushort v38, v134, s[4:5]
	s_add_u32 s4, s4, 0xc00
	s_addc_u32 s5, s5, 0
	global_load_ushort v39, v134, s[4:5]
	s_add_u32 s4, s4, 0xc00
	s_addc_u32 s5, s5, 0
	global_load_ushort v40, v134, s[4:5]
	s_add_u32 s4, s4, 0xc00
	s_addc_u32 s5, s5, 0
	global_load_ushort v41, v134, s[4:5]
	s_add_u32 s4, s4, 0xc00
	s_addc_u32 s5, s5, 0
	global_load_ushort v42, v134, s[4:5]
	s_add_u32 s4, s4, 0xc00
	s_addc_u32 s5, s5, 0
	global_load_ushort v43, v134, s[4:5]
	s_add_u32 s4, s4, 0xc00
	s_addc_u32 s5, s5, 0
	global_load_ushort v44, v134, s[4:5]
	s_add_u32 s4, s4, 0xc00
	s_addc_u32 s5, s5, 0
	global_load_ushort v45, v134, s[4:5]
	s_add_u32 s4, s4, 0xc00
	s_addc_u32 s5, s5, 0
	global_load_ushort v46, v134, s[4:5]
	s_add_u32 s4, s4, 0xc00
	s_addc_u32 s5, s5, 0
	global_load_ushort v47, v134, s[4:5]
	s_add_u32 s4, s4, 0xc00
	s_addc_u32 s5, s5, 0
	global_load_ushort v48, v134, s[4:5]
	s_add_u32 s4, s4, 0xc00
	s_addc_u32 s5, s5, 0
	global_load_ushort v49, v134, s[4:5]
	s_add_u32 s4, s4, 0xc00
	s_addc_u32 s5, s5, 0
	global_load_ushort v50, v134, s[4:5]
	s_add_u32 s4, s4, 0xc00
	s_addc_u32 s5, s5, 0
	global_load_ushort v51, v134, s[4:5]
	s_add_u32 s4, s4, 0xc00
	s_addc_u32 s5, s5, 0
	global_load_ushort v52, v134, s[4:5]
	s_add_u32 s4, s4, 0xc00
	s_addc_u32 s5, s5, 0
	global_load_ushort v53, v134, s[4:5]
	s_add_u32 s4, s4, 0xc00
	s_addc_u32 s5, s5, 0
	global_load_ushort v54, v134, s[4:5]
	s_add_u32 s4, s4, 0xc00
	s_addc_u32 s5, s5, 0
	global_load_ushort v55, v134, s[4:5]
	s_add_u32 s4, s4, 0xc00
	s_addc_u32 s5, s5, 0
	global_load_ushort v56, v134, s[4:5]
; __device__ __forceinline__ float bf2f(u16 h) { return __uint_as_float(((unsigned)h) << 16); }
; __device__ __forceinline__ void lru_tile(const Params& P, int chunk, int head, int pass, char* smem_raw) {
;     ...
;     const float w0 = P.conv_w[gch], w1 = P.conv_w[512 + gch], w2 = P.conv_w[1024 + gch], w3 = P.conv_w[1536 + gch];
;     const float cb = P.conv_b[gch];
;     const u16* zu = P.zq + gch;
;     const int r = row0 + q * 32;
;     float uv[35];
; #pragma unroll
;     for (int i = 0; i < 35; ++i) {
;       const int rr = r - 2 + i;
;       uv[i] = (rr >= seq_lo && rr < seq_hi) ? bf2f(zu[(long)rr * 1536]) : 0.f;
;     ...
;       *reinterpret_cast<uint4*>(&sm_w[rowi * LDSS + kg * 8]) = ldg16(P.wg + ((long)(d * 8 + head) * 128 + rowi) * 64 + kg * 8);
;     }
;     float ba[4], bi[4], c8[4];
; #pragma unroll
;     for (int tc = 0; tc < 4; ++tc) {
;       const int cidx = d * 512 + head * 64 + 16 * tc + (lane & 15);
;       ba[tc] = P.b_a[cidx] * -1.4426950408889634f; bi[tc] = P.b_i[cidx] * -1.4426950408889634f;
;       const float nl = -P.lam[cidx];
;       const float e_ = __expf(nl);
;       const float sp = (nl > 20.f) ? nl
;                      : (e_ < 0.03f ? e_ * (1.f - e_ * (0.5f - e_ * (0.33333334f - 0.25f * e_))) : __logf(1.f + e_));
;       c8[tc] = 8.f * 1.4426950408889634f * sp;
;     }
	s_add_u32 s4, s4, 0xc00
	s_addc_u32 s5, s5, 0
	global_load_ushort v57, v134, s[4:5]
	s_add_u32 s4, s4, 0xc00
	s_addc_u32 s5, s5, 0
	global_load_ushort v58, v134, s[4:5]
	s_add_u32 s4, s4, 0xc00
	s_addc_u32 s5, s5, 0
	global_load_ushort v59, v134, s[4:5]
	s_add_u32 s4, s4, 0xc00
	s_addc_u32 s5, s5, 0
	global_load_ushort v60, v134, s[4:5]
	s_add_u32 s4, s4, 0xc00
	s_addc_u32 s5, s5, 0
	global_load_ushort v61, v134, s[4:5]
	s_add_u32 s4, s4, 0xc00
	s_addc_u32 s5, s5, 0
	global_load_ushort v62, v134, s[4:5]
	s_add_u32 s4, s4, 0xc00
	s_addc_u32 s5, s5, 0
	global_load_ushort v63, v134, s[4:5]
	s_add_u32 s4, s4, 0xc00
	s_addc_u32 s5, s5, 0
	global_load_ushort v64, v134, s[4:5]
	s_add_u32 s4, s4, 0xc00
	s_addc_u32 s5, s5, 0
	global_load_ushort v66, v134, s[4:5]
	s_add_u32 s4, s4, 0xc00
	s_addc_u32 s5, s5, 0
	global_load_ushort v69, v151, s[4:5]
	v_and_b32_e32 v138, 15, v152
	v_bfe_u32 v139, v152, 6, 2
	v_lshl_add_u32 v138, v139, 4, v138
	v_bfe_u32 v139, v152, 4, 2
	v_mul_u32_u24_e32 v139, 0x1020, v139
	v_lshl_add_u32 v138, v138, 1, v139
	v_mul_u32_u24_e32 v139, 0x12000, v153
	v_add_u32_e32 v138, v138, v139
	v_add_u32_e32 v132, 0x4010, v138
	v_and_b32_e32 v138, 63, v152
	v_lshrrev_b32_e32 v139, 3, v138
	v_mul_u32_u24_e32 v139, 0xc00, v139
	v_and_b32_e32 v138, 7, v138
	v_lshl_add_u32 v135, v138, 4, v139
	v_readfirstlane_b32 s62, v153
	s_mul_i32 s62, s62, 0x12000
	s_add_u32 s62, s62, 0x4010
	v_readfirstlane_b32 s58, v204
	s_and_b32 s58, s58, 3
	s_mul_i32 s0, s59, 0x60000
	s_lshl_b32 s1, s56, 1
	s_add_u32 s0, s0, s1
	s_add_u32 s0, s0, 0x400
	s_mul_i32 s1, s58, 0x18000
	s_add_u32 s0, s0, s1
	s_add_u32 s4, s10, s0
	s_addc_u32 s5, s11, 0
	s_mul_i32 s60, s58, 0x1020
	s_add_u32 s60, s60, s62
	s_add_u32 m0, s60, 0x0
	s_nop 0
	global_load_lds_dwordx4 v135, s[4:5]
	s_add_u32 s4, s4, 0x6000
	s_addc_u32 s5, s5, 0
	s_add_u32 m0, s60, 0x400
	s_nop 0
	global_load_lds_dwordx4 v135, s[4:5]
	s_add_u32 s4, s4, 0x6000
	s_addc_u32 s5, s5, 0
	s_add_u32 m0, s60, 0x800
	s_nop 0
	global_load_lds_dwordx4 v135, s[4:5]
	s_add_u32 s4, s4, 0x6000
	s_addc_u32 s5, s5, 0
	s_add_u32 m0, s60, 0xc00
	s_nop 0
	global_load_lds_dwordx4 v135, s[4:5]
	v_bfe_u32 v255, v152, 6, 2
	v_and_b32_e32 v253, 15, v152
	v_lshl_add_u32 v255, v255, 4, v253
	v_add_u32_e32 v255, s56, v255
	v_lshlrev_b32_e32 v255, 2, v255
	global_load_dword v65, v255, s[24:25]
	global_load_dword v67, v255, s[24:25] offset:2048
	s_add_u32 s0, s24, 0x1000
	s_addc_u32 s1, s25, 0
	global_load_dword v68, v255, s[0:1]
	global_load_dword v70, v255, s[0:1] offset:2048
	global_load_dword v73, v255, s[26:27]
	s_add_u32 s0, s28, 0x0
	s_addc_u32 s1, s29, 0
	global_load_dword v75, v255, s[0:1]
	s_add_u32 s0, s30, 0x0
	s_addc_u32 s1, s31, 0
	global_load_dword v84, v255, s[0:1]
	s_add_u32 s0, s36, 0x0
	s_addc_u32 s1, s37, 0
	global_load_dword v85, v255, s[0:1]
	s_add_u32 s0, s28, 0x800
	s_addc_u32 s1, s29, 0
	global_load_dword v145, v255, s[0:1]
	s_add_u32 s0, s30, 0x800
	s_addc_u32 s1, s31, 0
	global_load_dword v146, v255, s[0:1]
	s_add_u32 s0, s36, 0x800
	s_addc_u32 s1, s37, 0
	global_load_dword v147, v255, s[0:1]
	s_lshl_b32 s0, s56, 8
	s_add_u32 s0, s0, 0x0
	s_add_u32 s4, s20, s0
	s_addc_u32 s5, s21, 0
	global_load_dwordx4 v[238:241], v251, s[4:5]
	global_load_dwordx4 v[242:245], v251, s[4:5] offset:64
	s_add_u32 s4, s4, 0x2000
	s_addc_u32 s5, s5, 0
	global_load_dwordx4 v[246:249], v251, s[4:5]
	global_load_dwordx4 v[194:197], v251, s[4:5] offset:64
	s_waitcnt vmcnt(0)
	v_mul_f32_e32 v75, 0xbfb8aa3b, v75
	v_mul_f32_e32 v84, 0xbfb8aa3b, v84
	v_sub_f32_e32 v138, 0, v85
	v_mul_f32_e32 v139, 0x3fb8aa3b, v138
	v_exp_f32_e32 v139, v139
	s_nop 0
	v_mul_f32_e32 v140, 0xbe800000, v139
	v_add_f32_e32 v140, 0x3eaaaaab, v140
	v_fma_f32 v140, -v139, v140, 0.5
	v_fma_f32 v140, -v139, v140, 1.0
	v_mul_f32_e32 v140, v139, v140
	v_add_f32_e32 v141, 1.0, v139
	v_log_f32_e32 v141, v141
	v_mov_b32_e32 v255, 0x3cf5c28f
	v_mul_f32_e32 v141, 0x3f317218, v141
	v_cmp_gt_f32_e32 vcc, v255, v139
	s_nop 1
	v_cndmask_b32_e32 v140, v141, v140, vcc
	v_mov_b32_e32 v255, 0x41a00000
	v_cmp_lt_f32_e32 vcc, v255, v138
	s_nop 1
	v_cndmask_b32_e32 v140, v140, v138, vcc
	v_mul_f32_e32 v85, 0xc138aa3b, v140
	v_mul_f32_e32 v145, 0xbfb8aa3b, v145
	v_mul_f32_e32 v146, 0xbfb8aa3b, v146
	v_sub_f32_e32 v138, 0, v147
	v_mul_f32_e32 v139, 0x3fb8aa3b, v138
	v_exp_f32_e32 v139, v139
	s_nop 0
	v_mul_f32_e32 v140, 0xbe800000, v139
	v_add_f32_e32 v140, 0x3eaaaaab, v140
	v_fma_f32 v140, -v139, v140, 0.5
	v_fma_f32 v140, -v139, v140, 1.0
	v_mul_f32_e32 v140, v139, v140
	v_add_f32_e32 v141, 1.0, v139
	v_log_f32_e32 v141, v141
	v_mov_b32_e32 v255, 0x3cf5c28f
	v_mul_f32_e32 v141, 0x3f317218, v141
	v_cmp_gt_f32_e32 vcc, v255, v139
	s_nop 1
	v_cndmask_b32_e32 v140, v141, v140, vcc
	v_mov_b32_e32 v255, 0x41a00000
	v_cmp_lt_f32_e32 vcc, v255, v138
	s_nop 1
	v_cndmask_b32_e32 v140, v140, v138, vcc
	v_mul_f32_e32 v147, 0xc138aa3b, v140

; __device__ __forceinline__ float bf2f(u16 h) { return __uint_as_float(((unsigned)h) << 16); }
; __device__ __forceinline__ void lru_tile(const Params& P, int chunk, int head, int pass, char* smem_raw) {
;     ...
;     const int r = row0 + q * 32;
;     float uv[35];
; #pragma unroll
;     for (int i = 0; i < 35; ++i) {
;       const int rr = r - 2 + i;
;       uv[i] = (rr >= seq_lo && rr < seq_hi) ? bf2f(zu[(long)rr * 1536]) : 0.f;
;     ...
;             const long rowp = row0 + sb * 64 + q * 16 + 15 - i;
;             hfp[i] = hfbuf[rowp * 512 + gch];
;             gp[i] = bf2f(P.zq[rowp * 1536 + 512 + gch]);
;           }
.Lmy_lrub_lb1_done:
	s_add_u32 s58, s69, 1
	s_cmp_lt_u32 s58, s70
	s_cbranch_scc0 .Lmy_lrub_nopf
	s_lshl_b32 s58, s58, 9
	s_add_u32 s58, s58, s68
	s_lshr_b32 s59, s58, 3
	s_cmp_lt_u32 s59, 256
	s_cselect_b32 s60, 63, 1
	s_and_b32 s57, s59, s60
	s_cmp_eq_u32 s57, 0
	s_cselect_b64 s[0:1], s[84:85], 0
	s_cmp_eq_u32 s57, s60
	s_cselect_b64 s[4:5], s[86:87], 0
	v_mov_b32_e32 v255, 0x1800
	v_cndmask_b32_e64 v150, 0, v255, s[0:1]
	v_lshlrev_b32_e32 v136, 1, v150
	v_add_u32_e32 v136, v134, v136
	v_add_u32_e32 v150, v134, v150
	v_cndmask_b32_e64 v151, 0, v255, s[4:5]
	v_sub_u32_e32 v151, v134, v151
	s_lshl_b32 s61, s59, 7
	s_mul_i32 s0, s61, 0xc00
	s_lshl_b32 s1, s56, 1
	s_add_u32 s0, s0, s1
	s_add_u32 s4, s10, s0
	s_addc_u32 s5, s11, 0
	s_sub_u32 s4, s4, 0x1800
	s_subb_u32 s5, s5, 0
	global_load_ushort v32, v136, s[4:5]
	s_add_u32 s4, s4, 0xc00
	s_addc_u32 s5, s5, 0
	global_load_ushort v33, v150, s[4:5]
	s_add_u32 s4, s4, 0xc00
	s_addc_u32 s5, s5, 0
	global_load_ushort v34, v134, s[4:5]
	s_add_u32 s4, s4, 0xc00
	s_addc_u32 s5, s5, 0
	global_load_ushort v35, v134, s[4:5]
	s_add_u32 s4, s4, 0xc00
	s_addc_u32 s5, s5, 0
	global_load_ushort v36, v134, s[4:5]
	s_add_u32 s4, s4, 0xc00
	s_addc_u32 s5, s5, 0
	global_load_ushort v37, v134, s[4:5]
	s_add_u32 s4, s4, 0xc00
	s_addc_u32 s5, s5, 0
	global_load_ushort v38, v134, s[4:5]
	s_add_u32 s4, s4, 0xc00
	s_addc_u32 s5, s5, 0
	global_load_ushort v39, v134, s[4:5]
	s_add_u32 s4, s4, 0xc00
	s_addc_u32 s5, s5, 0
	global_load_ushort v40, v134, s[4:5]
	s_add_u32 s4, s4, 0xc00
	s_addc_u32 s5, s5, 0
	global_load_ushort v41, v134, s[4:5]
	s_add_u32 s4, s4, 0xc00
	s_addc_u32 s5, s5, 0
	global_load_ushort v42, v134, s[4:5]
	s_add_u32 s4, s4, 0xc00
	s_addc_u32 s5, s5, 0
	global_load_ushort v43, v134, s[4:5]
	s_add_u32 s4, s4, 0xc00
	s_addc_u32 s5, s5, 0
	global_load_ushort v44, v134, s[4:5]
	s_add_u32 s4, s4, 0xc00
	s_addc_u32 s5, s5, 0
	global_load_ushort v45, v134, s[4:5]
	s_add_u32 s4, s4, 0xc00
	s_addc_u32 s5, s5, 0
	global_load_ushort v46, v134, s[4:5]
	s_add_u32 s4, s4, 0xc00
	s_addc_u32 s5, s5, 0
	global_load_ushort v47, v134, s[4:5]
	s_add_u32 s4, s4, 0xc00
	s_addc_u32 s5, s5, 0
	global_load_ushort v48, v134, s[4:5]
	s_add_u32 s4, s4, 0xc00
	s_addc_u32 s5, s5, 0
	global_load_ushort v49, v134, s[4:5]
	s_add_u32 s4, s4, 0xc00
	s_addc_u32 s5, s5, 0
	global_load_ushort v50, v134, s[4:5]
	s_add_u32 s4, s4, 0xc00
	s_addc_u32 s5, s5, 0
	global_load_ushort v51, v134, s[4:5]
	s_add_u32 s4, s4, 0xc00
	s_addc_u32 s5, s5, 0
	global_load_ushort v52, v134, s[4:5]
	s_add_u32 s4, s4, 0xc00
	s_addc_u32 s5, s5, 0
	global_load_ushort v53, v134, s[4:5]
	s_add_u32 s4, s4, 0xc00
	s_addc_u32 s5, s5, 0
	global_load_ushort v54, v134, s[4:5]
	s_add_u32 s4, s4, 0xc00
	s_addc_u32 s5, s5, 0
	global_load_ushort v55, v134, s[4:5]
	s_add_u32 s4, s4, 0xc00
	s_addc_u32 s5, s5, 0
	global_load_ushort v56, v134, s[4:5]
	s_add_u32 s4, s4, 0xc00
	s_addc_u32 s5, s5, 0
	global_load_ushort v57, v134, s[4:5]
	s_add_u32 s4, s4, 0xc00
	s_addc_u32 s5, s5, 0
	global_load_ushort v58, v134, s[4:5]
	s_add_u32 s4, s4, 0xc00
	s_addc_u32 s5, s5, 0
	global_load_ushort v59, v134, s[4:5]
	s_add_u32 s4, s4, 0xc00
	s_addc_u32 s5, s5, 0
	global_load_ushort v60, v134, s[4:5]
	s_add_u32 s4, s4, 0xc00
	s_addc_u32 s5, s5, 0
	global_load_ushort v61, v134, s[4:5]
	s_add_u32 s4, s4, 0xc00
	s_addc_u32 s5, s5, 0
	global_load_ushort v62, v134, s[4:5]
	s_add_u32 s4, s4, 0xc00
	s_addc_u32 s5, s5, 0
	global_load_ushort v63, v134, s[4:5]
	s_add_u32 s4, s4, 0xc00
	s_addc_u32 s5, s5, 0
	global_load_ushort v64, v134, s[4:5]
	s_add_u32 s4, s4, 0xc00
	s_addc_u32 s5, s5, 0
	global_load_ushort v66, v134, s[4:5]
	s_add_u32 s4, s4, 0xc00
	s_addc_u32 s5, s5, 0
	global_load_ushort v69, v151, s[4:5]
	v_readfirstlane_b32 s58, v204
	s_and_b32 s58, s58, 3
	s_mul_i32 s0, s59, 0x60000
	s_lshl_b32 s1, s56, 1
	s_add_u32 s0, s0, s1
	s_add_u32 s0, s0, 0x400
	s_mul_i32 s1, s58, 0x18000
	s_add_u32 s0, s0, s1
	s_add_u32 s4, s10, s0
	s_addc_u32 s5, s11, 0
	s_mul_i32 s60, s58, 0x1020
	s_add_u32 s60, s60, s62
	s_add_u32 s61, s69, 1
	s_and_b32 s61, s61, 1
	s_mul_i32 s61, s61, 0x4100
	s_add_u32 s60, s60, s61
	s_add_u32 m0, s60, 0x0
	s_nop 0
	global_load_lds_dwordx4 v135, s[4:5]
	s_add_u32 s4, s4, 0x6000
	s_addc_u32 s5, s5, 0
	s_add_u32 m0, s60, 0x400
	s_nop 0
	global_load_lds_dwordx4 v135, s[4:5]
	s_add_u32 s4, s4, 0x6000
	s_addc_u32 s5, s5, 0
	s_add_u32 m0, s60, 0x800
	s_nop 0
	global_load_lds_dwordx4 v135, s[4:5]
	s_add_u32 s4, s4, 0x6000
	s_addc_u32 s5, s5, 0
	s_add_u32 m0, s60, 0xc00
	s_nop 0
	global_load_lds_dwordx4 v135, s[4:5]
; __device__ __forceinline__ float bf2f(u16 h) { return __uint_as_float(((unsigned)h) << 16); }
; __device__ __forceinline__ void lru_tile(const Params& P, int chunk, int head, int pass, char* smem_raw) {
;     ...
;       for (int s = 0; s < 2; ++s) {
;         const bf16x8 af = *reinterpret_cast<const bf16x8*>(&sm_uc[(sb * 64 + wid * 16 + (lane & 15)) * LDSS + s * 32 + (lane >> 4) * 8]);
; #pragma unroll
;         for (int t = 0; t < 8; ++t) {
;           const bf16x8 bfr = *reinterpret_cast<const bf16x8*>(&sm_w[(t * 16 + (lane & 15)) * LDSS + s * 32 + (lane >> 4) * 8]);
;           acc[t] = __builtin_amdgcn_mfma_f32_16x16x32_bf16(af, bfr, acc[t], 0, 0, 0);
;         }
;       }
; #pragma unroll
;       for (int tc = 0; tc < 4; ++tc)
; #pragma unroll
;         for (int reg = 0; reg < 4; ++reg) {
;           const int tl = wid * 16 + (lane >> 4) * 4 + reg;
;           const int c = 16 * tc + (lane & 15);
;           const float r = __builtin_amdgcn_rcpf(1.f + __builtin_amdgcn_exp2f(acc[tc][reg] + ba[tc]));
;           const float ii = __builtin_amdgcn_rcpf(1.f + __builtin_amdgcn_exp2f(acc[tc + 4][reg] + bi[tc]));
;           const float la = -c8[tc] * r;
;           const float a = __builtin_amdgcn_exp2f(la);
;           const float ucv = bf2f(sm_uc[(sb * 64 + tl) * LDSS + c]);
;           const float bt = __builtin_amdgcn_sqrtf(fmaxf(1.f - a * a, 0.f)) * (ii * ucv);
;           sm_a[tl * 64 + c] = a;
;           sm_b[tl * 64 + c] = bt;
.Lmy_lrub_nopf:
	ds_read_b128 v[76:79], v131 offset:0
	ds_read_b128 v[80:83], v133 offset:0
	ds_read_b128 v[122:125], v131 offset:512
	ds_read_b128 v[126:129], v133 offset:512
	s_waitcnt lgkmcnt(3)
	v_mfma_f32_16x16x32_bf16 v[0:3], v[76:79], v[238:241], 0
	v_mfma_f32_16x16x32_bf16 v[90:93], v[76:79], v[246:249], 0
	ds_read_b128 v[76:79], v131 offset:1024
	s_waitcnt lgkmcnt(3)
	v_mfma_f32_16x16x32_bf16 v[0:3], v[80:83], v[242:245], v[0:3]
	v_mfma_f32_16x16x32_bf16 v[90:93], v[80:83], v[194:197], v[90:93]
	ds_read_b128 v[80:83], v133 offset:1024
	s_waitcnt lgkmcnt(3)
	v_mfma_f32_16x16x32_bf16 v[4:7], v[122:125], v[238:241], 0
	v_mfma_f32_16x16x32_bf16 v[94:97], v[122:125], v[246:249], 0
	ds_read_b128 v[122:125], v131 offset:1536
	s_waitcnt lgkmcnt(3)
	v_mfma_f32_16x16x32_bf16 v[4:7], v[126:129], v[242:245], v[4:7]
	v_mfma_f32_16x16x32_bf16 v[94:97], v[126:129], v[194:197], v[94:97]
	ds_read_b128 v[126:129], v133 offset:1536
	s_waitcnt lgkmcnt(3)
	v_mfma_f32_16x16x32_bf16 v[8:11], v[76:79], v[238:241], 0
	v_mfma_f32_16x16x32_bf16 v[98:101], v[76:79], v[246:249], 0
	ds_read_b128 v[76:79], v131 offset:2048
	s_waitcnt lgkmcnt(3)
	v_mfma_f32_16x16x32_bf16 v[8:11], v[80:83], v[242:245], v[8:11]
	v_mfma_f32_16x16x32_bf16 v[98:101], v[80:83], v[194:197], v[98:101]
	ds_read_b128 v[80:83], v133 offset:2048
	s_waitcnt lgkmcnt(3)
	v_mfma_f32_16x16x32_bf16 v[12:15], v[122:125], v[238:241], 0
	v_mfma_f32_16x16x32_bf16 v[102:105], v[122:125], v[246:249], 0
	ds_read_b128 v[122:125], v131 offset:2560
	s_waitcnt lgkmcnt(3)
	v_mfma_f32_16x16x32_bf16 v[12:15], v[126:129], v[242:245], v[12:15]
	v_mfma_f32_16x16x32_bf16 v[102:105], v[126:129], v[194:197], v[102:105]
	ds_read_b128 v[126:129], v133 offset:2560
	s_waitcnt lgkmcnt(3)
	v_mfma_f32_16x16x32_bf16 v[16:19], v[76:79], v[238:241], 0
	v_mfma_f32_16x16x32_bf16 v[106:109], v[76:79], v[246:249], 0
	ds_read_b128 v[76:79], v131 offset:3072
	s_waitcnt lgkmcnt(3)
	v_mfma_f32_16x16x32_bf16 v[16:19], v[80:83], v[242:245], v[16:19]
	v_mfma_f32_16x16x32_bf16 v[106:109], v[80:83], v[194:197], v[106:109]
	ds_read_b128 v[80:83], v133 offset:3072
	s_waitcnt lgkmcnt(3)
	v_mfma_f32_16x16x32_bf16 v[20:23], v[122:125], v[238:241], 0
	v_mfma_f32_16x16x32_bf16 v[110:113], v[122:125], v[246:249], 0
	ds_read_b128 v[122:125], v131 offset:3584
	s_waitcnt lgkmcnt(3)
	v_mfma_f32_16x16x32_bf16 v[20:23], v[126:129], v[242:245], v[20:23]
	v_mfma_f32_16x16x32_bf16 v[110:113], v[126:129], v[194:197], v[110:113]
	ds_read_b128 v[126:129], v133 offset:3584
	s_waitcnt lgkmcnt(3)
	v_mfma_f32_16x16x32_bf16 v[24:27], v[76:79], v[238:241], 0
	v_mfma_f32_16x16x32_bf16 v[114:117], v[76:79], v[246:249], 0
	s_waitcnt lgkmcnt(2)
	v_mfma_f32_16x16x32_bf16 v[24:27], v[80:83], v[242:245], v[24:27]
	v_mfma_f32_16x16x32_bf16 v[114:117], v[80:83], v[194:197], v[114:117]
	s_waitcnt lgkmcnt(1)
	v_mfma_f32_16x16x32_bf16 v[28:31], v[122:125], v[238:241], 0
	v_mfma_f32_16x16x32_bf16 v[118:121], v[122:125], v[246:249], 0
	s_waitcnt lgkmcnt(0)
	v_mfma_f32_16x16x32_bf16 v[28:31], v[126:129], v[242:245], v[28:31]
	v_mfma_f32_16x16x32_bf16 v[118:121], v[126:129], v[194:197], v[118:121]
	s_lshl_b32 s0, s56, 8
	s_add_u32 s0, s0, 0x20000
	s_add_u32 s4, s20, s0
	s_addc_u32 s5, s21, 0
	global_load_dwordx4 v[238:241], v251, s[4:5]
	global_load_dwordx4 v[242:245], v251, s[4:5] offset:64
	s_add_u32 s4, s4, 0x2000
	s_addc_u32 s5, s5, 0
	global_load_dwordx4 v[246:249], v251, s[4:5]
	global_load_dwordx4 v[194:197], v251, s[4:5] offset:64
	s_nop 7
	s_nop 7
	v_add_f32_e32 v0, v0, v75
	v_add_f32_e32 v1, v1, v75
	v_add_f32_e32 v2, v2, v75
	v_add_f32_e32 v3, v3, v75
	v_add_f32_e32 v90, v90, v84
	v_add_f32_e32 v91, v91, v84
	v_add_f32_e32 v92, v92, v84
	v_add_f32_e32 v93, v93, v84
	v_exp_f32_e32 v0, v0
	v_exp_f32_e32 v1, v1
	v_exp_f32_e32 v2, v2
	v_exp_f32_e32 v3, v3
	v_exp_f32_e32 v90, v90
	v_exp_f32_e32 v91, v91
	v_exp_f32_e32 v92, v92
	v_exp_f32_e32 v93, v93
	v_add_f32_e32 v0, 1.0, v0
	v_add_f32_e32 v1, 1.0, v1
	v_add_f32_e32 v2, 1.0, v2
	v_add_f32_e32 v3, 1.0, v3
	v_add_f32_e32 v90, 1.0, v90
	v_add_f32_e32 v91, 1.0, v91
	v_add_f32_e32 v92, 1.0, v92
	v_add_f32_e32 v93, 1.0, v93
	v_rcp_f32_e32 v0, v0
	v_rcp_f32_e32 v1, v1
	v_rcp_f32_e32 v2, v2
	v_rcp_f32_e32 v3, v3
	v_rcp_f32_e32 v90, v90
	v_rcp_f32_e32 v91, v91
	v_rcp_f32_e32 v92, v92
	v_rcp_f32_e32 v93, v93
	v_mul_f32_e32 v0, v85, v0
	v_mul_f32_e32 v1, v85, v1
	v_mul_f32_e32 v2, v85, v2
	v_mul_f32_e32 v3, v85, v3
	v_mul_f32_e32 v90, v90, v162
	v_mul_f32_e32 v91, v91, v163
	v_mul_f32_e32 v92, v92, v164
	v_mul_f32_e32 v93, v93, v165
	v_exp_f32_e32 v0, v0
	v_exp_f32_e32 v1, v1
	v_exp_f32_e32 v2, v2
	v_exp_f32_e32 v3, v3
	s_nop 0
	v_fma_f32 v138, -v0, v0, 1.0
	v_fma_f32 v139, -v1, v1, 1.0
	v_fma_f32 v140, -v2, v2, 1.0
	v_fma_f32 v141, -v3, v3, 1.0
	v_max_f32_e32 v138, 0, v138
	v_max_f32_e32 v139, 0, v139
	v_max_f32_e32 v140, 0, v140
	v_max_f32_e32 v141, 0, v141
	v_sqrt_f32_e32 v138, v138
	v_sqrt_f32_e32 v139, v139
	v_sqrt_f32_e32 v140, v140
	v_sqrt_f32_e32 v141, v141
	s_nop 0
	v_mul_f32_e32 v90, v138, v90
	v_mul_f32_e32 v91, v139, v91
	v_mul_f32_e32 v92, v140, v92
	v_mul_f32_e32 v93, v141, v93
	v_add_f32_e32 v4, v4, v75
	v_add_f32_e32 v5, v5, v75
	v_add_f32_e32 v6, v6, v75
	v_add_f32_e32 v7, v7, v75
	v_add_f32_e32 v94, v94, v84
	v_add_f32_e32 v95, v95, v84
	v_add_f32_e32 v96, v96, v84
	v_add_f32_e32 v97, v97, v84
	v_exp_f32_e32 v4, v4
	v_exp_f32_e32 v5, v5
	v_exp_f32_e32 v6, v6
	v_exp_f32_e32 v7, v7
	v_exp_f32_e32 v94, v94
	v_exp_f32_e32 v95, v95
	v_exp_f32_e32 v96, v96
	v_exp_f32_e32 v97, v97
	v_add_f32_e32 v4, 1.0, v4
	v_add_f32_e32 v5, 1.0, v5
	v_add_f32_e32 v6, 1.0, v6
	v_add_f32_e32 v7, 1.0, v7
	v_add_f32_e32 v94, 1.0, v94
; __device__ __forceinline__ float bf2f(u16 h) { return __uint_as_float(((unsigned)h) << 16); }
; __device__ __forceinline__ void lru_tile(const Params& P, int chunk, int head, int pass, char* smem_raw) {
;     ...
;       for (int tc = 0; tc < 4; ++tc)
; #pragma unroll
;         for (int reg = 0; reg < 4; ++reg) {
;           const int tl = wid * 16 + (lane >> 4) * 4 + reg;
;           const int c = 16 * tc + (lane & 15);
;           const float r = __builtin_amdgcn_rcpf(1.f + __builtin_amdgcn_exp2f(acc[tc][reg] + ba[tc]));
;           const float ii = __builtin_amdgcn_rcpf(1.f + __builtin_amdgcn_exp2f(acc[tc + 4][reg] + bi[tc]));
;           const float la = -c8[tc] * r;
;           const float a = __builtin_amdgcn_exp2f(la);
;           const float ucv = bf2f(sm_uc[(sb * 64 + tl) * LDSS + c]);
;           const float bt = __builtin_amdgcn_sqrtf(fmaxf(1.f - a * a, 0.f)) * (ii * ucv);
;           sm_a[tl * 64 + c] = a;
;           sm_b[tl * 64 + c] = bt;
	v_add_f32_e32 v95, 1.0, v95
	v_add_f32_e32 v96, 1.0, v96
	v_add_f32_e32 v97, 1.0, v97
	v_rcp_f32_e32 v4, v4
	v_rcp_f32_e32 v5, v5
	v_rcp_f32_e32 v6, v6
	v_rcp_f32_e32 v7, v7
	v_rcp_f32_e32 v94, v94
	v_rcp_f32_e32 v95, v95
	v_rcp_f32_e32 v96, v96
	v_rcp_f32_e32 v97, v97
	v_mul_f32_e32 v4, v85, v4
	v_mul_f32_e32 v5, v85, v5
	v_mul_f32_e32 v6, v85, v6
	v_mul_f32_e32 v7, v85, v7
	v_mul_f32_e32 v94, v94, v166
	v_mul_f32_e32 v95, v95, v167
	v_mul_f32_e32 v96, v96, v168
	v_mul_f32_e32 v97, v97, v169
	v_exp_f32_e32 v4, v4
	v_exp_f32_e32 v5, v5
	v_exp_f32_e32 v6, v6
	v_exp_f32_e32 v7, v7
	s_nop 0
	v_fma_f32 v138, -v4, v4, 1.0
	v_fma_f32 v139, -v5, v5, 1.0
	v_fma_f32 v140, -v6, v6, 1.0
	v_fma_f32 v141, -v7, v7, 1.0
	v_max_f32_e32 v138, 0, v138
	v_max_f32_e32 v139, 0, v139
	v_max_f32_e32 v140, 0, v140
	v_max_f32_e32 v141, 0, v141
	v_sqrt_f32_e32 v138, v138
	v_sqrt_f32_e32 v139, v139
	v_sqrt_f32_e32 v140, v140
	v_sqrt_f32_e32 v141, v141
	s_nop 0
	v_mul_f32_e32 v94, v138, v94
	v_mul_f32_e32 v95, v139, v95
	v_mul_f32_e32 v96, v140, v96
	v_mul_f32_e32 v97, v141, v97
	v_add_f32_e32 v8, v8, v75
	v_add_f32_e32 v9, v9, v75
	v_add_f32_e32 v10, v10, v75
	v_add_f32_e32 v11, v11, v75
	v_add_f32_e32 v98, v98, v84
	v_add_f32_e32 v99, v99, v84
	v_add_f32_e32 v100, v100, v84
	v_add_f32_e32 v101, v101, v84
	v_exp_f32_e32 v8, v8
	v_exp_f32_e32 v9, v9
	v_exp_f32_e32 v10, v10
	v_exp_f32_e32 v11, v11
	v_exp_f32_e32 v98, v98
	v_exp_f32_e32 v99, v99
	v_exp_f32_e32 v100, v100
	v_exp_f32_e32 v101, v101
	v_add_f32_e32 v8, 1.0, v8
	v_add_f32_e32 v9, 1.0, v9
	v_add_f32_e32 v10, 1.0, v10
	v_add_f32_e32 v11, 1.0, v11
	v_add_f32_e32 v98, 1.0, v98
	v_add_f32_e32 v99, 1.0, v99
	v_add_f32_e32 v100, 1.0, v100
	v_add_f32_e32 v101, 1.0, v101
	v_rcp_f32_e32 v8, v8
	v_rcp_f32_e32 v9, v9
	v_rcp_f32_e32 v10, v10
	v_rcp_f32_e32 v11, v11
	v_rcp_f32_e32 v98, v98
	v_rcp_f32_e32 v99, v99
	v_rcp_f32_e32 v100, v100
	v_rcp_f32_e32 v101, v101
	v_mul_f32_e32 v8, v85, v8
	v_mul_f32_e32 v9, v85, v9
	v_mul_f32_e32 v10, v85, v10
	v_mul_f32_e32 v11, v85, v11
	v_mul_f32_e32 v98, v98, v170
	v_mul_f32_e32 v99, v99, v171
	v_mul_f32_e32 v100, v100, v172
	v_mul_f32_e32 v101, v101, v173
	v_exp_f32_e32 v8, v8
	v_exp_f32_e32 v9, v9
	v_exp_f32_e32 v10, v10
	v_exp_f32_e32 v11, v11
	s_nop 0
	v_fma_f32 v138, -v8, v8, 1.0
	v_fma_f32 v139, -v9, v9, 1.0
	v_fma_f32 v140, -v10, v10, 1.0
	v_fma_f32 v141, -v11, v11, 1.0
	v_max_f32_e32 v138, 0, v138
	v_max_f32_e32 v139, 0, v139
	v_max_f32_e32 v140, 0, v140
	v_max_f32_e32 v141, 0, v141
	v_sqrt_f32_e32 v138, v138
	v_sqrt_f32_e32 v139, v139
	v_sqrt_f32_e32 v140, v140
	v_sqrt_f32_e32 v141, v141
	s_nop 0
	v_mul_f32_e32 v98, v138, v98
	v_mul_f32_e32 v99, v139, v99
	v_mul_f32_e32 v100, v140, v100
	v_mul_f32_e32 v101, v141, v101
	v_add_f32_e32 v12, v12, v75
	v_add_f32_e32 v13, v13, v75
	v_add_f32_e32 v14, v14, v75
	v_add_f32_e32 v15, v15, v75
	v_add_f32_e32 v102, v102, v84
	v_add_f32_e32 v103, v103, v84
	v_add_f32_e32 v104, v104, v84
	v_add_f32_e32 v105, v105, v84
	v_exp_f32_e32 v12, v12
	v_exp_f32_e32 v13, v13
	v_exp_f32_e32 v14, v14
	v_exp_f32_e32 v15, v15
	v_exp_f32_e32 v102, v102
	v_exp_f32_e32 v103, v103
	v_exp_f32_e32 v104, v104
	v_exp_f32_e32 v105, v105
	v_add_f32_e32 v12, 1.0, v12
	v_add_f32_e32 v13, 1.0, v13
	v_add_f32_e32 v14, 1.0, v14
	v_add_f32_e32 v15, 1.0, v15
	v_add_f32_e32 v102, 1.0, v102
	v_add_f32_e32 v103, 1.0, v103
	v_add_f32_e32 v104, 1.0, v104
	v_add_f32_e32 v105, 1.0, v105
	v_rcp_f32_e32 v12, v12
	v_rcp_f32_e32 v13, v13
	v_rcp_f32_e32 v14, v14
	v_rcp_f32_e32 v15, v15
	v_rcp_f32_e32 v102, v102
	v_rcp_f32_e32 v103, v103
	v_rcp_f32_e32 v104, v104
	v_rcp_f32_e32 v105, v105
	v_mul_f32_e32 v12, v85, v12
	v_mul_f32_e32 v13, v85, v13
	v_mul_f32_e32 v14, v85, v14
	v_mul_f32_e32 v15, v85, v15
	v_mul_f32_e32 v102, v102, v174
	v_mul_f32_e32 v103, v103, v175
	v_mul_f32_e32 v104, v104, v176
	v_mul_f32_e32 v105, v105, v177
	v_exp_f32_e32 v12, v12
	v_exp_f32_e32 v13, v13
	v_exp_f32_e32 v14, v14
	v_exp_f32_e32 v15, v15
	s_nop 0
	v_fma_f32 v138, -v12, v12, 1.0
	v_fma_f32 v139, -v13, v13, 1.0
	v_fma_f32 v140, -v14, v14, 1.0
	v_fma_f32 v141, -v15, v15, 1.0
	v_max_f32_e32 v138, 0, v138
	v_max_f32_e32 v139, 0, v139
	v_max_f32_e32 v140, 0, v140
	v_max_f32_e32 v141, 0, v141
	v_sqrt_f32_e32 v138, v138
	v_sqrt_f32_e32 v139, v139
	v_sqrt_f32_e32 v140, v140
	v_sqrt_f32_e32 v141, v141
	s_nop 0
	v_mul_f32_e32 v102, v138, v102
	v_mul_f32_e32 v103, v139, v103
	v_mul_f32_e32 v104, v140, v104
	v_mul_f32_e32 v105, v141, v105
	v_add_f32_e32 v16, v16, v75
	v_add_f32_e32 v17, v17, v75
	v_add_f32_e32 v18, v18, v75
	v_add_f32_e32 v19, v19, v75
	v_add_f32_e32 v106, v106, v84
	v_add_f32_e32 v107, v107, v84
	v_add_f32_e32 v108, v108, v84
	v_add_f32_e32 v109, v109, v84
	v_exp_f32_e32 v16, v16
	v_exp_f32_e32 v17, v17
	v_exp_f32_e32 v18, v18
	v_exp_f32_e32 v19, v19
	v_exp_f32_e32 v106, v106
	v_exp_f32_e32 v107, v107
	v_exp_f32_e32 v108, v108
	v_exp_f32_e32 v109, v109
	v_add_f32_e32 v16, 1.0, v16
	v_add_f32_e32 v17, 1.0, v17
	v_add_f32_e32 v18, 1.0, v18
	v_add_f32_e32 v19, 1.0, v19
	v_add_f32_e32 v106, 1.0, v106
	v_add_f32_e32 v107, 1.0, v107
	v_add_f32_e32 v108, 1.0, v108
	v_add_f32_e32 v109, 1.0, v109
	v_rcp_f32_e32 v16, v16
	v_rcp_f32_e32 v17, v17
	v_rcp_f32_e32 v18, v18
	v_rcp_f32_e32 v19, v19
	v_rcp_f32_e32 v106, v106
	v_rcp_f32_e32 v107, v107
	v_rcp_f32_e32 v108, v108
	v_rcp_f32_e32 v109, v109
	v_mul_f32_e32 v16, v85, v16
	v_mul_f32_e32 v17, v85, v17
	v_mul_f32_e32 v18, v85, v18
	v_mul_f32_e32 v19, v85, v19
	v_mul_f32_e32 v106, v106, v178
	v_mul_f32_e32 v107, v107, v179
	v_mul_f32_e32 v108, v108, v180
	v_mul_f32_e32 v109, v109, v181
	v_exp_f32_e32 v16, v16
	v_exp_f32_e32 v17, v17
	v_exp_f32_e32 v18, v18
; __device__ __forceinline__ float bf2f(u16 h) { return __uint_as_float(((unsigned)h) << 16); }
; __device__ __forceinline__ void lru_tile(const Params& P, int chunk, int head, int pass, char* smem_raw) {
;     ...
;       for (int tc = 0; tc < 4; ++tc)
; #pragma unroll
;         for (int reg = 0; reg < 4; ++reg) {
;           const int tl = wid * 16 + (lane >> 4) * 4 + reg;
;           const int c = 16 * tc + (lane & 15);
;           const float r = __builtin_amdgcn_rcpf(1.f + __builtin_amdgcn_exp2f(acc[tc][reg] + ba[tc]));
;           const float ii = __builtin_amdgcn_rcpf(1.f + __builtin_amdgcn_exp2f(acc[tc + 4][reg] + bi[tc]));
;           const float la = -c8[tc] * r;
;           const float a = __builtin_amdgcn_exp2f(la);
;           const float ucv = bf2f(sm_uc[(sb * 64 + tl) * LDSS + c]);
;           const float bt = __builtin_amdgcn_sqrtf(fmaxf(1.f - a * a, 0.f)) * (ii * ucv);
;           sm_a[tl * 64 + c] = a;
;           sm_b[tl * 64 + c] = bt;
	v_exp_f32_e32 v19, v19
	s_nop 0
	v_fma_f32 v138, -v16, v16, 1.0
	v_fma_f32 v139, -v17, v17, 1.0
	v_fma_f32 v140, -v18, v18, 1.0
	v_fma_f32 v141, -v19, v19, 1.0
	v_max_f32_e32 v138, 0, v138
	v_max_f32_e32 v139, 0, v139
	v_max_f32_e32 v140, 0, v140
	v_max_f32_e32 v141, 0, v141
	v_sqrt_f32_e32 v138, v138
	v_sqrt_f32_e32 v139, v139
	v_sqrt_f32_e32 v140, v140
	v_sqrt_f32_e32 v141, v141
	s_nop 0
	v_mul_f32_e32 v106, v138, v106
	v_mul_f32_e32 v107, v139, v107
	v_mul_f32_e32 v108, v140, v108
	v_mul_f32_e32 v109, v141, v109
	v_add_f32_e32 v20, v20, v75
	v_add_f32_e32 v21, v21, v75
	v_add_f32_e32 v22, v22, v75
	v_add_f32_e32 v23, v23, v75
	v_add_f32_e32 v110, v110, v84
	v_add_f32_e32 v111, v111, v84
	v_add_f32_e32 v112, v112, v84
	v_add_f32_e32 v113, v113, v84
	v_exp_f32_e32 v20, v20
	v_exp_f32_e32 v21, v21
	v_exp_f32_e32 v22, v22
	v_exp_f32_e32 v23, v23
	v_exp_f32_e32 v110, v110
	v_exp_f32_e32 v111, v111
	v_exp_f32_e32 v112, v112
	v_exp_f32_e32 v113, v113
	v_add_f32_e32 v20, 1.0, v20
	v_add_f32_e32 v21, 1.0, v21
	v_add_f32_e32 v22, 1.0, v22
	v_add_f32_e32 v23, 1.0, v23
	v_add_f32_e32 v110, 1.0, v110
	v_add_f32_e32 v111, 1.0, v111
	v_add_f32_e32 v112, 1.0, v112
	v_add_f32_e32 v113, 1.0, v113
	v_rcp_f32_e32 v20, v20
	v_rcp_f32_e32 v21, v21
	v_rcp_f32_e32 v22, v22
	v_rcp_f32_e32 v23, v23
	v_rcp_f32_e32 v110, v110
	v_rcp_f32_e32 v111, v111
	v_rcp_f32_e32 v112, v112
	v_rcp_f32_e32 v113, v113
	v_mul_f32_e32 v20, v85, v20
	v_mul_f32_e32 v21, v85, v21
	v_mul_f32_e32 v22, v85, v22
	v_mul_f32_e32 v23, v85, v23
	v_mul_f32_e32 v110, v110, v182
	v_mul_f32_e32 v111, v111, v183
	v_mul_f32_e32 v112, v112, v184
	v_mul_f32_e32 v113, v113, v185
	v_exp_f32_e32 v20, v20
	v_exp_f32_e32 v21, v21
	v_exp_f32_e32 v22, v22
	v_exp_f32_e32 v23, v23
	s_nop 0
	v_fma_f32 v138, -v20, v20, 1.0
	v_fma_f32 v139, -v21, v21, 1.0
	v_fma_f32 v140, -v22, v22, 1.0
	v_fma_f32 v141, -v23, v23, 1.0
	v_max_f32_e32 v138, 0, v138
	v_max_f32_e32 v139, 0, v139
	v_max_f32_e32 v140, 0, v140
	v_max_f32_e32 v141, 0, v141
	v_sqrt_f32_e32 v138, v138
	v_sqrt_f32_e32 v139, v139
	v_sqrt_f32_e32 v140, v140
	v_sqrt_f32_e32 v141, v141
	s_nop 0
	v_mul_f32_e32 v110, v138, v110
	v_mul_f32_e32 v111, v139, v111
	v_mul_f32_e32 v112, v140, v112
	v_mul_f32_e32 v113, v141, v113
	v_add_f32_e32 v24, v24, v75
	v_add_f32_e32 v25, v25, v75
	v_add_f32_e32 v26, v26, v75
	v_add_f32_e32 v27, v27, v75
	v_add_f32_e32 v114, v114, v84
	v_add_f32_e32 v115, v115, v84
	v_add_f32_e32 v116, v116, v84
	v_add_f32_e32 v117, v117, v84
	v_exp_f32_e32 v24, v24
	v_exp_f32_e32 v25, v25
	v_exp_f32_e32 v26, v26
	v_exp_f32_e32 v27, v27
	v_exp_f32_e32 v114, v114
	v_exp_f32_e32 v115, v115
	v_exp_f32_e32 v116, v116
	v_exp_f32_e32 v117, v117
	v_add_f32_e32 v24, 1.0, v24
	v_add_f32_e32 v25, 1.0, v25
	v_add_f32_e32 v26, 1.0, v26
	v_add_f32_e32 v27, 1.0, v27
	v_add_f32_e32 v114, 1.0, v114
	v_add_f32_e32 v115, 1.0, v115
	v_add_f32_e32 v116, 1.0, v116
	v_add_f32_e32 v117, 1.0, v117
	v_rcp_f32_e32 v24, v24
	v_rcp_f32_e32 v25, v25
	v_rcp_f32_e32 v26, v26
	v_rcp_f32_e32 v27, v27
	v_rcp_f32_e32 v114, v114
	v_rcp_f32_e32 v115, v115
	v_rcp_f32_e32 v116, v116
	v_rcp_f32_e32 v117, v117
	v_mul_f32_e32 v24, v85, v24
	v_mul_f32_e32 v25, v85, v25
	v_mul_f32_e32 v26, v85, v26
	v_mul_f32_e32 v27, v85, v27
	v_mul_f32_e32 v114, v114, v186
	v_mul_f32_e32 v115, v115, v187
	v_mul_f32_e32 v116, v116, v188
	v_mul_f32_e32 v117, v117, v189
	v_exp_f32_e32 v24, v24
	v_exp_f32_e32 v25, v25
	v_exp_f32_e32 v26, v26
	v_exp_f32_e32 v27, v27
	s_nop 0
	v_fma_f32 v138, -v24, v24, 1.0
	v_fma_f32 v139, -v25, v25, 1.0
	v_fma_f32 v140, -v26, v26, 1.0
	v_fma_f32 v141, -v27, v27, 1.0
	v_max_f32_e32 v138, 0, v138
	v_max_f32_e32 v139, 0, v139
	v_max_f32_e32 v140, 0, v140
	v_max_f32_e32 v141, 0, v141
	v_sqrt_f32_e32 v138, v138
	v_sqrt_f32_e32 v139, v139
	v_sqrt_f32_e32 v140, v140
	v_sqrt_f32_e32 v141, v141
	s_nop 0
	v_mul_f32_e32 v114, v138, v114
	v_mul_f32_e32 v115, v139, v115
	v_mul_f32_e32 v116, v140, v116
	v_mul_f32_e32 v117, v141, v117
	v_add_f32_e32 v28, v28, v75
	v_add_f32_e32 v29, v29, v75
	v_add_f32_e32 v30, v30, v75
	v_add_f32_e32 v31, v31, v75
	v_add_f32_e32 v118, v118, v84
	v_add_f32_e32 v119, v119, v84
	v_add_f32_e32 v120, v120, v84
	v_add_f32_e32 v121, v121, v84
	v_exp_f32_e32 v28, v28
	v_exp_f32_e32 v29, v29
	v_exp_f32_e32 v30, v30
	v_exp_f32_e32 v31, v31
	v_exp_f32_e32 v118, v118
	v_exp_f32_e32 v119, v119
	v_exp_f32_e32 v120, v120
	v_exp_f32_e32 v121, v121
	v_add_f32_e32 v28, 1.0, v28
	v_add_f32_e32 v29, 1.0, v29
	v_add_f32_e32 v30, 1.0, v30
	v_add_f32_e32 v31, 1.0, v31
	v_add_f32_e32 v118, 1.0, v118
	v_add_f32_e32 v119, 1.0, v119
	v_add_f32_e32 v120, 1.0, v120
	v_add_f32_e32 v121, 1.0, v121
	v_rcp_f32_e32 v28, v28
	v_rcp_f32_e32 v29, v29
	v_rcp_f32_e32 v30, v30
	v_rcp_f32_e32 v31, v31
	v_rcp_f32_e32 v118, v118
	v_rcp_f32_e32 v119, v119
	v_rcp_f32_e32 v120, v120
	v_rcp_f32_e32 v121, v121
	v_mul_f32_e32 v28, v85, v28
	v_mul_f32_e32 v29, v85, v29
	v_mul_f32_e32 v30, v85, v30
	v_mul_f32_e32 v31, v85, v31
	v_mul_f32_e32 v118, v118, v190
	v_mul_f32_e32 v119, v119, v191
	v_mul_f32_e32 v120, v120, v192
	v_mul_f32_e32 v121, v121, v193
	v_exp_f32_e32 v28, v28
	v_exp_f32_e32 v29, v29
	v_exp_f32_e32 v30, v30
	v_exp_f32_e32 v31, v31
	s_nop 0
	v_fma_f32 v138, -v28, v28, 1.0
	v_fma_f32 v139, -v29, v29, 1.0
	v_fma_f32 v140, -v30, v30, 1.0
	v_fma_f32 v141, -v31, v31, 1.0
	v_max_f32_e32 v138, 0, v138
	v_max_f32_e32 v139, 0, v139
	v_max_f32_e32 v140, 0, v140
	v_max_f32_e32 v141, 0, v141
	v_sqrt_f32_e32 v138, v138
	v_sqrt_f32_e32 v139, v139
	v_sqrt_f32_e32 v140, v140
	v_sqrt_f32_e32 v141, v141
	s_nop 0
	v_mul_f32_e32 v118, v138, v118
	v_mul_f32_e32 v119, v139, v119
	v_mul_f32_e32 v120, v140, v120
; __device__ __forceinline__ float bf2f(u16 h) { return __uint_as_float(((unsigned)h) << 16); }
; __device__ __forceinline__ void lru_tile(const Params& P, int chunk, int head, int pass, char* smem_raw) {
;     ...
;       for (int s = 0; s < 2; ++s) {
;         const bf16x8 af = *reinterpret_cast<const bf16x8*>(&sm_uc[(sb * 64 + wid * 16 + (lane & 15)) * LDSS + s * 32 + (lane >> 4) * 8]);
; #pragma unroll
;         for (int t = 0; t < 8; ++t) {
;           const bf16x8 bfr = *reinterpret_cast<const bf16x8*>(&sm_w[(t * 16 + (lane & 15)) * LDSS + s * 32 + (lane >> 4) * 8]);
;           acc[t] = __builtin_amdgcn_mfma_f32_16x16x32_bf16(af, bfr, acc[t], 0, 0, 0);
;         }
;     ...
;       const int pos = (d == 0) ? q : 3 - q;
;       {
;         float Pp = 1.f, H = 0.f;
; #pragma unroll 4
;         for (int i = 0; i < 16; ++i) {
;           const int tl = (d == 0) ? (q * 16 + i) : (q * 16 + 15 - i);
;           const float a = sm_a[tl * 64 + ch], b = sm_b[tl * 64 + ch];
;           H = a * H + b; Pp *= a;
;         }
;         sm_ph[pos * 64 + ch] = make_float2(Pp, H);
;       }
;       __syncthreads();
;       const float2 p0 = sm_ph[ch], p1 = sm_ph[64 + ch], p2 = sm_ph[128 + ch], p3 = sm_ph[192 + ch];
;       if (pass == 2) {
;         float hin = cB;
;         if (pos > 0) hin = p0.x * hin + p0.y;
;         if (pos > 1) hin = p1.x * hin + p1.y;
;         if (pos > 2) hin = p2.x * hin + p2.y;
;         float h = hin;
;         float hfp[16], gp[16];
;         if (d == 1) {
; #pragma unroll
;           for (int i = 0; i < 16; ++i) {
;             const long rowp = row0 + sb * 64 + q * 16 + 15 - i;
;             hfp[i] = hfbuf[rowp * 512 + gch];
;             gp[i] = bf2f(P.zq[rowp * 1536 + 512 + gch]);
;           }
;         }
; #pragma unroll
;         for (int i = 0; i < 16; ++i) {
;           const int tl = (d == 0) ? (q * 16 + i) : (q * 16 + 15 - i);
;           const float a = sm_a[tl * 64 + ch], b = sm_b[tl * 64 + ch];
;           h = a * h + b;
;           const long row = row0 + sb * 64 + tl;
;           if (d == 0) {
;             hfw[row * 512 + gch] = h;
	v_mul_f32_e32 v121, v141, v121
	v_mov_b32_e32 v253, v0
	v_mov_b32_e32 v254, v90
	v_fma_f32 v254, v1, v254, v91
	v_mul_f32_e32 v253, v253, v1
	v_fma_f32 v254, v2, v254, v92
	v_mul_f32_e32 v253, v253, v2
	v_fma_f32 v254, v3, v254, v93
	v_mul_f32_e32 v253, v253, v3
	v_fma_f32 v254, v4, v254, v94
	v_mul_f32_e32 v253, v253, v4
	v_fma_f32 v254, v5, v254, v95
	v_mul_f32_e32 v253, v253, v5
	v_fma_f32 v254, v6, v254, v96
	v_mul_f32_e32 v253, v253, v6
	v_fma_f32 v254, v7, v254, v97
	v_mul_f32_e32 v253, v253, v7
	v_fma_f32 v254, v8, v254, v98
	v_mul_f32_e32 v253, v253, v8
	v_fma_f32 v254, v9, v254, v99
	v_mul_f32_e32 v253, v253, v9
	v_fma_f32 v254, v10, v254, v100
	v_mul_f32_e32 v253, v253, v10
	v_fma_f32 v254, v11, v254, v101
	v_mul_f32_e32 v253, v253, v11
	v_fma_f32 v254, v12, v254, v102
	v_mul_f32_e32 v253, v253, v12
	v_fma_f32 v254, v13, v254, v103
	v_mul_f32_e32 v253, v253, v13
	v_fma_f32 v254, v14, v254, v104
	v_mul_f32_e32 v253, v253, v14
	v_fma_f32 v254, v15, v254, v105
	v_mul_f32_e32 v253, v253, v15
	v_fma_f32 v254, v16, v254, v106
	v_mul_f32_e32 v253, v253, v16
	v_fma_f32 v254, v17, v254, v107
	v_mul_f32_e32 v253, v253, v17
	v_fma_f32 v254, v18, v254, v108
	v_mul_f32_e32 v253, v253, v18
	v_fma_f32 v254, v19, v254, v109
	v_mul_f32_e32 v253, v253, v19
	v_fma_f32 v254, v20, v254, v110
	v_mul_f32_e32 v253, v253, v20
	v_fma_f32 v254, v21, v254, v111
	v_mul_f32_e32 v253, v253, v21
	v_fma_f32 v254, v22, v254, v112
	v_mul_f32_e32 v253, v253, v22
	v_fma_f32 v254, v23, v254, v113
	v_mul_f32_e32 v253, v253, v23
	v_fma_f32 v254, v24, v254, v114
	v_mul_f32_e32 v253, v253, v24
	v_fma_f32 v254, v25, v254, v115
	v_mul_f32_e32 v253, v253, v25
	v_fma_f32 v254, v26, v254, v116
	v_mul_f32_e32 v253, v253, v26
	v_fma_f32 v254, v27, v254, v117
	v_mul_f32_e32 v253, v253, v27
	v_fma_f32 v254, v28, v254, v118
	v_mul_f32_e32 v253, v253, v28
	v_fma_f32 v254, v29, v254, v119
	v_mul_f32_e32 v253, v253, v29
	v_fma_f32 v254, v30, v254, v120
	v_mul_f32_e32 v253, v253, v30
	v_fma_f32 v254, v31, v254, v121
	v_mul_f32_e32 v253, v253, v31
	v_mov_b32_e32 v138, v253
	v_mov_b32_e32 v139, v253
	s_nop 1
	v_permlane16_swap_b32_e32 v138, v139
	v_mov_b32_e32 v140, v138
	v_mov_b32_e32 v141, v139
	s_nop 1
	v_permlane32_swap_b32_e32 v138, v140
	v_permlane32_swap_b32_e32 v139, v141
	v_mov_b32_e32 v198, v254
	v_mov_b32_e32 v199, v254
	s_nop 1
	v_permlane16_swap_b32_e32 v198, v199
	v_mov_b32_e32 v200, v198
	v_mov_b32_e32 v201, v199
	s_nop 1
	v_permlane32_swap_b32_e32 v198, v200
	v_permlane32_swap_b32_e32 v199, v201
	v_mov_b32_e32 v136, v148
	v_fma_f32 v150, v138, v136, v198
	v_fma_f32 v151, v139, v150, v199
	v_fma_f32 v202, v140, v151, v200
	v_mov_b32_e32 v254, v136
	v_cndmask_b32_e64 v254, v254, v150, s[72:73]
	v_cndmask_b32_e64 v254, v254, v151, s[74:75]
	v_cndmask_b32_e64 v254, v254, v202, s[76:77]
	v_fma_f32 v205, v0, v254, v90
	v_fma_f32 v206, v1, v205, v91
	v_fma_f32 v207, v2, v206, v92
	v_fma_f32 v208, v3, v207, v93
	v_fma_f32 v209, v4, v208, v94
	v_fma_f32 v210, v5, v209, v95
	v_fma_f32 v211, v6, v210, v96
	v_fma_f32 v212, v7, v211, v97
	v_fma_f32 v213, v8, v212, v98
	v_fma_f32 v214, v9, v213, v99
	v_fma_f32 v215, v10, v214, v100
	v_fma_f32 v216, v11, v215, v101
	v_fma_f32 v217, v12, v216, v102
	v_fma_f32 v218, v13, v217, v103
	v_fma_f32 v219, v14, v218, v104
	v_fma_f32 v220, v15, v219, v105
	v_fma_f32 v221, v16, v220, v106
	v_fma_f32 v222, v17, v221, v107
	v_fma_f32 v223, v18, v222, v108
	v_fma_f32 v224, v19, v223, v109
	v_fma_f32 v225, v20, v224, v110
	v_fma_f32 v226, v21, v225, v111
	v_fma_f32 v227, v22, v226, v112
	v_fma_f32 v228, v23, v227, v113
	v_fma_f32 v229, v24, v228, v114
	v_fma_f32 v230, v25, v229, v115
	v_fma_f32 v231, v26, v230, v116
	v_fma_f32 v232, v27, v231, v117
	v_fma_f32 v233, v28, v232, v118
	v_fma_f32 v234, v29, v233, v119
	v_fma_f32 v235, v30, v234, v120
	v_fma_f32 v236, v31, v235, v121
	ds_read_b128 v[76:79], v131 offset:0
	ds_read_b128 v[80:83], v133 offset:0
	ds_read_b128 v[122:125], v131 offset:512
	ds_read_b128 v[126:129], v133 offset:512
	s_waitcnt vmcnt(0)
	s_waitcnt lgkmcnt(3)
	v_mfma_f32_16x16x32_bf16 v[0:3], v[76:79], v[238:241], 0
	v_mfma_f32_16x16x32_bf16 v[90:93], v[76:79], v[246:249], 0
	ds_read_b128 v[76:79], v131 offset:1024
	s_waitcnt lgkmcnt(3)
	v_mfma_f32_16x16x32_bf16 v[0:3], v[80:83], v[242:245], v[0:3]
	v_mfma_f32_16x16x32_bf16 v[90:93], v[80:83], v[194:197], v[90:93]
	ds_read_b128 v[80:83], v133 offset:1024
	s_waitcnt lgkmcnt(3)
	v_mfma_f32_16x16x32_bf16 v[4:7], v[122:125], v[238:241], 0
	v_mfma_f32_16x16x32_bf16 v[94:97], v[122:125], v[246:249], 0
	ds_read_b128 v[122:125], v131 offset:1536
	s_waitcnt lgkmcnt(3)
	v_mfma_f32_16x16x32_bf16 v[4:7], v[126:129], v[242:245], v[4:7]
	v_mfma_f32_16x16x32_bf16 v[94:97], v[126:129], v[194:197], v[94:97]
	ds_read_b128 v[126:129], v133 offset:1536
	s_waitcnt lgkmcnt(3)
	v_mfma_f32_16x16x32_bf16 v[8:11], v[76:79], v[238:241], 0
	v_mfma_f32_16x16x32_bf16 v[98:101], v[76:79], v[246:249], 0
	ds_read_b128 v[76:79], v131 offset:2048
	s_waitcnt lgkmcnt(3)
	v_mfma_f32_16x16x32_bf16 v[8:11], v[80:83], v[242:245], v[8:11]
	v_mfma_f32_16x16x32_bf16 v[98:101], v[80:83], v[194:197], v[98:101]
	ds_read_b128 v[80:83], v133 offset:2048
	s_waitcnt lgkmcnt(3)
	v_mfma_f32_16x16x32_bf16 v[12:15], v[122:125], v[238:241], 0
	v_mfma_f32_16x16x32_bf16 v[102:105], v[122:125], v[246:249], 0
	ds_read_b128 v[122:125], v131 offset:2560
	s_waitcnt lgkmcnt(3)
	v_mfma_f32_16x16x32_bf16 v[12:15], v[126:129], v[242:245], v[12:15]
	v_mfma_f32_16x16x32_bf16 v[102:105], v[126:129], v[194:197], v[102:105]
	ds_read_b128 v[126:129], v133 offset:2560
	s_waitcnt lgkmcnt(3)
; __device__ __forceinline__ float bf2f(u16 h) { return __uint_as_float(((unsigned)h) << 16); }
; __device__ __forceinline__ void lru_tile(const Params& P, int chunk, int head, int pass, char* smem_raw) {
;     ...
;       for (int s = 0; s < 2; ++s) {
;         const bf16x8 af = *reinterpret_cast<const bf16x8*>(&sm_uc[(sb * 64 + wid * 16 + (lane & 15)) * LDSS + s * 32 + (lane >> 4) * 8]);
; #pragma unroll
;         for (int t = 0; t < 8; ++t) {
;           const bf16x8 bfr = *reinterpret_cast<const bf16x8*>(&sm_w[(t * 16 + (lane & 15)) * LDSS + s * 32 + (lane >> 4) * 8]);
;           acc[t] = __builtin_amdgcn_mfma_f32_16x16x32_bf16(af, bfr, acc[t], 0, 0, 0);
;         }
;       }
; #pragma unroll
;       for (int tc = 0; tc < 4; ++tc)
; #pragma unroll
;         for (int reg = 0; reg < 4; ++reg) {
;           const int tl = wid * 16 + (lane >> 4) * 4 + reg;
;           const int c = 16 * tc + (lane & 15);
;           const float r = __builtin_amdgcn_rcpf(1.f + __builtin_amdgcn_exp2f(acc[tc][reg] + ba[tc]));
;           const float ii = __builtin_amdgcn_rcpf(1.f + __builtin_amdgcn_exp2f(acc[tc + 4][reg] + bi[tc]));
;           const float la = -c8[tc] * r;
;           const float a = __builtin_amdgcn_exp2f(la);
;           const float ucv = bf2f(sm_uc[(sb * 64 + tl) * LDSS + c]);
;           const float bt = __builtin_amdgcn_sqrtf(fmaxf(1.f - a * a, 0.f)) * (ii * ucv);
;           sm_a[tl * 64 + c] = a;
;           sm_b[tl * 64 + c] = bt;
	v_mfma_f32_16x16x32_bf16 v[16:19], v[76:79], v[238:241], 0
	v_mfma_f32_16x16x32_bf16 v[106:109], v[76:79], v[246:249], 0
	ds_read_b128 v[76:79], v131 offset:3072
	s_waitcnt lgkmcnt(3)
	v_mfma_f32_16x16x32_bf16 v[16:19], v[80:83], v[242:245], v[16:19]
	v_mfma_f32_16x16x32_bf16 v[106:109], v[80:83], v[194:197], v[106:109]
	ds_read_b128 v[80:83], v133 offset:3072
	s_waitcnt lgkmcnt(3)
	v_mfma_f32_16x16x32_bf16 v[20:23], v[122:125], v[238:241], 0
	v_mfma_f32_16x16x32_bf16 v[110:113], v[122:125], v[246:249], 0
	ds_read_b128 v[122:125], v131 offset:3584
	s_waitcnt lgkmcnt(3)
	v_mfma_f32_16x16x32_bf16 v[20:23], v[126:129], v[242:245], v[20:23]
	v_mfma_f32_16x16x32_bf16 v[110:113], v[126:129], v[194:197], v[110:113]
	ds_read_b128 v[126:129], v133 offset:3584
	s_waitcnt lgkmcnt(3)
	v_mfma_f32_16x16x32_bf16 v[24:27], v[76:79], v[238:241], 0
	v_mfma_f32_16x16x32_bf16 v[114:117], v[76:79], v[246:249], 0
	s_waitcnt lgkmcnt(2)
	v_mfma_f32_16x16x32_bf16 v[24:27], v[80:83], v[242:245], v[24:27]
	v_mfma_f32_16x16x32_bf16 v[114:117], v[80:83], v[194:197], v[114:117]
	s_waitcnt lgkmcnt(1)
	v_mfma_f32_16x16x32_bf16 v[28:31], v[122:125], v[238:241], 0
	v_mfma_f32_16x16x32_bf16 v[118:121], v[122:125], v[246:249], 0
	s_waitcnt lgkmcnt(0)
	v_mfma_f32_16x16x32_bf16 v[28:31], v[126:129], v[242:245], v[28:31]
	v_mfma_f32_16x16x32_bf16 v[118:121], v[126:129], v[194:197], v[118:121]
	s_lshl_b32 s0, s56, 8
	s_add_u32 s0, s0, 0x0
	s_add_u32 s4, s20, s0
	s_addc_u32 s5, s21, 0
	global_load_dwordx4 v[238:241], v251, s[4:5]
	global_load_dwordx4 v[242:245], v251, s[4:5] offset:64
	s_add_u32 s4, s4, 0x2000
	s_addc_u32 s5, s5, 0
	global_load_dwordx4 v[246:249], v251, s[4:5]
	global_load_dwordx4 v[194:197], v251, s[4:5] offset:64
	s_nop 7
	s_nop 7
	v_add_f32_e32 v0, v0, v145
	v_add_f32_e32 v1, v1, v145
	v_add_f32_e32 v2, v2, v145
	v_add_f32_e32 v3, v3, v145
	v_add_f32_e32 v90, v90, v146
	v_add_f32_e32 v91, v91, v146
	v_add_f32_e32 v92, v92, v146
	v_add_f32_e32 v93, v93, v146
	v_exp_f32_e32 v0, v0
	v_exp_f32_e32 v1, v1
	v_exp_f32_e32 v2, v2
	v_exp_f32_e32 v3, v3
	v_exp_f32_e32 v90, v90
	v_exp_f32_e32 v91, v91
	v_exp_f32_e32 v92, v92
	v_exp_f32_e32 v93, v93
	v_add_f32_e32 v0, 1.0, v0
	v_add_f32_e32 v1, 1.0, v1
	v_add_f32_e32 v2, 1.0, v2
	v_add_f32_e32 v3, 1.0, v3
	v_add_f32_e32 v90, 1.0, v90
	v_add_f32_e32 v91, 1.0, v91
	v_add_f32_e32 v92, 1.0, v92
	v_add_f32_e32 v93, 1.0, v93
	v_rcp_f32_e32 v0, v0
	v_rcp_f32_e32 v1, v1
	v_rcp_f32_e32 v2, v2
	v_rcp_f32_e32 v3, v3
	v_rcp_f32_e32 v90, v90
	v_rcp_f32_e32 v91, v91
	v_rcp_f32_e32 v92, v92
	v_rcp_f32_e32 v93, v93
	v_mul_f32_e32 v0, v147, v0
	v_mul_f32_e32 v1, v147, v1
	v_mul_f32_e32 v2, v147, v2
	v_mul_f32_e32 v3, v147, v3
	v_mul_f32_e32 v90, v90, v162
	v_mul_f32_e32 v91, v91, v163
	v_mul_f32_e32 v92, v92, v164
	v_mul_f32_e32 v93, v93, v165
	v_exp_f32_e32 v0, v0
	v_exp_f32_e32 v1, v1
	v_exp_f32_e32 v2, v2
	v_exp_f32_e32 v3, v3
	s_nop 0
	v_fma_f32 v138, -v0, v0, 1.0
	v_fma_f32 v139, -v1, v1, 1.0
	v_fma_f32 v140, -v2, v2, 1.0
	v_fma_f32 v141, -v3, v3, 1.0
	v_max_f32_e32 v138, 0, v138
	v_max_f32_e32 v139, 0, v139
	v_max_f32_e32 v140, 0, v140
	v_max_f32_e32 v141, 0, v141
	v_sqrt_f32_e32 v138, v138
	v_sqrt_f32_e32 v139, v139
	v_sqrt_f32_e32 v140, v140
	v_sqrt_f32_e32 v141, v141
	s_nop 0
	v_mul_f32_e32 v90, v138, v90
	v_mul_f32_e32 v91, v139, v91
	v_mul_f32_e32 v92, v140, v92
	v_mul_f32_e32 v93, v141, v93
	v_add_f32_e32 v4, v4, v145
	v_add_f32_e32 v5, v5, v145
	v_add_f32_e32 v6, v6, v145
	v_add_f32_e32 v7, v7, v145
	v_add_f32_e32 v94, v94, v146
	v_add_f32_e32 v95, v95, v146
	v_add_f32_e32 v96, v96, v146
	v_add_f32_e32 v97, v97, v146
	v_exp_f32_e32 v4, v4
	v_exp_f32_e32 v5, v5
	v_exp_f32_e32 v6, v6
	v_exp_f32_e32 v7, v7
	v_exp_f32_e32 v94, v94
	v_exp_f32_e32 v95, v95
	v_exp_f32_e32 v96, v96
	v_exp_f32_e32 v97, v97
	v_add_f32_e32 v4, 1.0, v4
	v_add_f32_e32 v5, 1.0, v5
	v_add_f32_e32 v6, 1.0, v6
	v_add_f32_e32 v7, 1.0, v7
	v_add_f32_e32 v94, 1.0, v94
	v_add_f32_e32 v95, 1.0, v95
	v_add_f32_e32 v96, 1.0, v96
	v_add_f32_e32 v97, 1.0, v97
	v_rcp_f32_e32 v4, v4
	v_rcp_f32_e32 v5, v5
	v_rcp_f32_e32 v6, v6
	v_rcp_f32_e32 v7, v7
	v_rcp_f32_e32 v94, v94
	v_rcp_f32_e32 v95, v95
	v_rcp_f32_e32 v96, v96
	v_rcp_f32_e32 v97, v97
	v_mul_f32_e32 v4, v147, v4
	v_mul_f32_e32 v5, v147, v5
	v_mul_f32_e32 v6, v147, v6
	v_mul_f32_e32 v7, v147, v7
	v_mul_f32_e32 v94, v94, v166
	v_mul_f32_e32 v95, v95, v167
	v_mul_f32_e32 v96, v96, v168
	v_mul_f32_e32 v97, v97, v169
	v_exp_f32_e32 v4, v4
	v_exp_f32_e32 v5, v5
	v_exp_f32_e32 v6, v6
	v_exp_f32_e32 v7, v7
	s_nop 0
	v_fma_f32 v138, -v4, v4, 1.0
	v_fma_f32 v139, -v5, v5, 1.0
	v_fma_f32 v140, -v6, v6, 1.0
	v_fma_f32 v141, -v7, v7, 1.0
	v_max_f32_e32 v138, 0, v138
	v_max_f32_e32 v139, 0, v139
	v_max_f32_e32 v140, 0, v140
	v_max_f32_e32 v141, 0, v141
	v_sqrt_f32_e32 v138, v138
	v_sqrt_f32_e32 v139, v139
	v_sqrt_f32_e32 v140, v140
	v_sqrt_f32_e32 v141, v141
	s_nop 0
	v_mul_f32_e32 v94, v138, v94
	v_mul_f32_e32 v95, v139, v95
	v_mul_f32_e32 v96, v140, v96
	v_mul_f32_e32 v97, v141, v97
	v_add_f32_e32 v8, v8, v145
	v_add_f32_e32 v9, v9, v145
	v_add_f32_e32 v10, v10, v145
	v_add_f32_e32 v11, v11, v145
	v_add_f32_e32 v98, v98, v146
	v_add_f32_e32 v99, v99, v146
	v_add_f32_e32 v100, v100, v146
	v_add_f32_e32 v101, v101, v146
	v_exp_f32_e32 v8, v8
	v_exp_f32_e32 v9, v9
	v_exp_f32_e32 v10, v10
	v_exp_f32_e32 v11, v11
	v_exp_f32_e32 v98, v98
	v_exp_f32_e32 v99, v99
	v_exp_f32_e32 v100, v100
	v_exp_f32_e32 v101, v101
	v_add_f32_e32 v8, 1.0, v8
	v_add_f32_e32 v9, 1.0, v9
	v_add_f32_e32 v10, 1.0, v10
	v_add_f32_e32 v11, 1.0, v11
	v_add_f32_e32 v98, 1.0, v98
	v_add_f32_e32 v99, 1.0, v99
	v_add_f32_e32 v100, 1.0, v100
; __device__ __forceinline__ float bf2f(u16 h) { return __uint_as_float(((unsigned)h) << 16); }
; __device__ __forceinline__ void lru_tile(const Params& P, int chunk, int head, int pass, char* smem_raw) {
;     ...
;       for (int tc = 0; tc < 4; ++tc)
; #pragma unroll
;         for (int reg = 0; reg < 4; ++reg) {
;           const int tl = wid * 16 + (lane >> 4) * 4 + reg;
;           const int c = 16 * tc + (lane & 15);
;           const float r = __builtin_amdgcn_rcpf(1.f + __builtin_amdgcn_exp2f(acc[tc][reg] + ba[tc]));
;           const float ii = __builtin_amdgcn_rcpf(1.f + __builtin_amdgcn_exp2f(acc[tc + 4][reg] + bi[tc]));
;           const float la = -c8[tc] * r;
;           const float a = __builtin_amdgcn_exp2f(la);
;           const float ucv = bf2f(sm_uc[(sb * 64 + tl) * LDSS + c]);
;           const float bt = __builtin_amdgcn_sqrtf(fmaxf(1.f - a * a, 0.f)) * (ii * ucv);
;           sm_a[tl * 64 + c] = a;
;           sm_b[tl * 64 + c] = bt;
	v_add_f32_e32 v101, 1.0, v101
	v_rcp_f32_e32 v8, v8
	v_rcp_f32_e32 v9, v9
	v_rcp_f32_e32 v10, v10
	v_rcp_f32_e32 v11, v11
	v_rcp_f32_e32 v98, v98
	v_rcp_f32_e32 v99, v99
	v_rcp_f32_e32 v100, v100
	v_rcp_f32_e32 v101, v101
	v_mul_f32_e32 v8, v147, v8
	v_mul_f32_e32 v9, v147, v9
	v_mul_f32_e32 v10, v147, v10
	v_mul_f32_e32 v11, v147, v11
	v_mul_f32_e32 v98, v98, v170
	v_mul_f32_e32 v99, v99, v171
	v_mul_f32_e32 v100, v100, v172
	v_mul_f32_e32 v101, v101, v173
	v_exp_f32_e32 v8, v8
	v_exp_f32_e32 v9, v9
	v_exp_f32_e32 v10, v10
	v_exp_f32_e32 v11, v11
	s_nop 0
	v_fma_f32 v138, -v8, v8, 1.0
	v_fma_f32 v139, -v9, v9, 1.0
	v_fma_f32 v140, -v10, v10, 1.0
	v_fma_f32 v141, -v11, v11, 1.0
	v_max_f32_e32 v138, 0, v138
	v_max_f32_e32 v139, 0, v139
	v_max_f32_e32 v140, 0, v140
	v_max_f32_e32 v141, 0, v141
	v_sqrt_f32_e32 v138, v138
	v_sqrt_f32_e32 v139, v139
	v_sqrt_f32_e32 v140, v140
	v_sqrt_f32_e32 v141, v141
	s_nop 0
	v_mul_f32_e32 v98, v138, v98
	v_mul_f32_e32 v99, v139, v99
	v_mul_f32_e32 v100, v140, v100
	v_mul_f32_e32 v101, v141, v101
	v_add_f32_e32 v12, v12, v145
	v_add_f32_e32 v13, v13, v145
	v_add_f32_e32 v14, v14, v145
	v_add_f32_e32 v15, v15, v145
	v_add_f32_e32 v102, v102, v146
	v_add_f32_e32 v103, v103, v146
	v_add_f32_e32 v104, v104, v146
	v_add_f32_e32 v105, v105, v146
	v_exp_f32_e32 v12, v12
	v_exp_f32_e32 v13, v13
	v_exp_f32_e32 v14, v14
	v_exp_f32_e32 v15, v15
	v_exp_f32_e32 v102, v102
	v_exp_f32_e32 v103, v103
	v_exp_f32_e32 v104, v104
	v_exp_f32_e32 v105, v105
	v_add_f32_e32 v12, 1.0, v12
	v_add_f32_e32 v13, 1.0, v13
	v_add_f32_e32 v14, 1.0, v14
	v_add_f32_e32 v15, 1.0, v15
	v_add_f32_e32 v102, 1.0, v102
	v_add_f32_e32 v103, 1.0, v103
	v_add_f32_e32 v104, 1.0, v104
	v_add_f32_e32 v105, 1.0, v105
	v_rcp_f32_e32 v12, v12
	v_rcp_f32_e32 v13, v13
	v_rcp_f32_e32 v14, v14
	v_rcp_f32_e32 v15, v15
	v_rcp_f32_e32 v102, v102
	v_rcp_f32_e32 v103, v103
	v_rcp_f32_e32 v104, v104
	v_rcp_f32_e32 v105, v105
	v_mul_f32_e32 v12, v147, v12
	v_mul_f32_e32 v13, v147, v13
	v_mul_f32_e32 v14, v147, v14
	v_mul_f32_e32 v15, v147, v15
	v_mul_f32_e32 v102, v102, v174
	v_mul_f32_e32 v103, v103, v175
	v_mul_f32_e32 v104, v104, v176
	v_mul_f32_e32 v105, v105, v177
	v_exp_f32_e32 v12, v12
	v_exp_f32_e32 v13, v13
	v_exp_f32_e32 v14, v14
	v_exp_f32_e32 v15, v15
	s_nop 0
	v_fma_f32 v138, -v12, v12, 1.0
	v_fma_f32 v139, -v13, v13, 1.0
	v_fma_f32 v140, -v14, v14, 1.0
	v_fma_f32 v141, -v15, v15, 1.0
	v_max_f32_e32 v138, 0, v138
	v_max_f32_e32 v139, 0, v139
	v_max_f32_e32 v140, 0, v140
	v_max_f32_e32 v141, 0, v141
	v_sqrt_f32_e32 v138, v138
	v_sqrt_f32_e32 v139, v139
	v_sqrt_f32_e32 v140, v140
	v_sqrt_f32_e32 v141, v141
	s_nop 0
	v_mul_f32_e32 v102, v138, v102
	v_mul_f32_e32 v103, v139, v103
	v_mul_f32_e32 v104, v140, v104
	v_mul_f32_e32 v105, v141, v105
	v_add_f32_e32 v16, v16, v145
	v_add_f32_e32 v17, v17, v145
	v_add_f32_e32 v18, v18, v145
	v_add_f32_e32 v19, v19, v145
	v_add_f32_e32 v106, v106, v146
	v_add_f32_e32 v107, v107, v146
	v_add_f32_e32 v108, v108, v146
	v_add_f32_e32 v109, v109, v146
	v_exp_f32_e32 v16, v16
	v_exp_f32_e32 v17, v17
	v_exp_f32_e32 v18, v18
	v_exp_f32_e32 v19, v19
	v_exp_f32_e32 v106, v106
	v_exp_f32_e32 v107, v107
	v_exp_f32_e32 v108, v108
	v_exp_f32_e32 v109, v109
	v_add_f32_e32 v16, 1.0, v16
	v_add_f32_e32 v17, 1.0, v17
	v_add_f32_e32 v18, 1.0, v18
	v_add_f32_e32 v19, 1.0, v19
	v_add_f32_e32 v106, 1.0, v106
	v_add_f32_e32 v107, 1.0, v107
	v_add_f32_e32 v108, 1.0, v108
	v_add_f32_e32 v109, 1.0, v109
	v_rcp_f32_e32 v16, v16
	v_rcp_f32_e32 v17, v17
	v_rcp_f32_e32 v18, v18
	v_rcp_f32_e32 v19, v19
	v_rcp_f32_e32 v106, v106
	v_rcp_f32_e32 v107, v107
	v_rcp_f32_e32 v108, v108
	v_rcp_f32_e32 v109, v109
	v_mul_f32_e32 v16, v147, v16
	v_mul_f32_e32 v17, v147, v17
	v_mul_f32_e32 v18, v147, v18
	v_mul_f32_e32 v19, v147, v19
	v_mul_f32_e32 v106, v106, v178
	v_mul_f32_e32 v107, v107, v179
	v_mul_f32_e32 v108, v108, v180
	v_mul_f32_e32 v109, v109, v181
	v_exp_f32_e32 v16, v16
	v_exp_f32_e32 v17, v17
	v_exp_f32_e32 v18, v18
	v_exp_f32_e32 v19, v19
	s_nop 0
	v_fma_f32 v138, -v16, v16, 1.0
	v_fma_f32 v139, -v17, v17, 1.0
	v_fma_f32 v140, -v18, v18, 1.0
	v_fma_f32 v141, -v19, v19, 1.0
	v_max_f32_e32 v138, 0, v138
	v_max_f32_e32 v139, 0, v139
	v_max_f32_e32 v140, 0, v140
	v_max_f32_e32 v141, 0, v141
	v_sqrt_f32_e32 v138, v138
	v_sqrt_f32_e32 v139, v139
	v_sqrt_f32_e32 v140, v140
	v_sqrt_f32_e32 v141, v141
	s_nop 0
	v_mul_f32_e32 v106, v138, v106
	v_mul_f32_e32 v107, v139, v107
	v_mul_f32_e32 v108, v140, v108
	v_mul_f32_e32 v109, v141, v109
	v_add_f32_e32 v20, v20, v145
	v_add_f32_e32 v21, v21, v145
	v_add_f32_e32 v22, v22, v145
	v_add_f32_e32 v23, v23, v145
	v_add_f32_e32 v110, v110, v146
	v_add_f32_e32 v111, v111, v146
	v_add_f32_e32 v112, v112, v146
	v_add_f32_e32 v113, v113, v146
	v_exp_f32_e32 v20, v20
	v_exp_f32_e32 v21, v21
	v_exp_f32_e32 v22, v22
	v_exp_f32_e32 v23, v23
	v_exp_f32_e32 v110, v110
	v_exp_f32_e32 v111, v111
	v_exp_f32_e32 v112, v112
	v_exp_f32_e32 v113, v113
	v_add_f32_e32 v20, 1.0, v20
	v_add_f32_e32 v21, 1.0, v21
	v_add_f32_e32 v22, 1.0, v22
	v_add_f32_e32 v23, 1.0, v23
	v_add_f32_e32 v110, 1.0, v110
	v_add_f32_e32 v111, 1.0, v111
	v_add_f32_e32 v112, 1.0, v112
	v_add_f32_e32 v113, 1.0, v113
	v_rcp_f32_e32 v20, v20
	v_rcp_f32_e32 v21, v21
	v_rcp_f32_e32 v22, v22
	v_rcp_f32_e32 v23, v23
	v_rcp_f32_e32 v110, v110
	v_rcp_f32_e32 v111, v111
	v_rcp_f32_e32 v112, v112
	v_rcp_f32_e32 v113, v113
	v_mul_f32_e32 v20, v147, v20
	v_mul_f32_e32 v21, v147, v21
	v_mul_f32_e32 v22, v147, v22
	v_mul_f32_e32 v23, v147, v23
	v_mul_f32_e32 v110, v110, v182
	v_mul_f32_e32 v111, v111, v183
	v_mul_f32_e32 v112, v112, v184
	v_mul_f32_e32 v113, v113, v185
; __device__ __forceinline__ float bf2f(u16 h) { return __uint_as_float(((unsigned)h) << 16); }
; __device__ __forceinline__ void lru_tile(const Params& P, int chunk, int head, int pass, char* smem_raw) {
;     ...
;       for (int tc = 0; tc < 4; ++tc)
; #pragma unroll
;         for (int reg = 0; reg < 4; ++reg) {
;           const int tl = wid * 16 + (lane >> 4) * 4 + reg;
;           const int c = 16 * tc + (lane & 15);
;           const float r = __builtin_amdgcn_rcpf(1.f + __builtin_amdgcn_exp2f(acc[tc][reg] + ba[tc]));
;           const float ii = __builtin_amdgcn_rcpf(1.f + __builtin_amdgcn_exp2f(acc[tc + 4][reg] + bi[tc]));
;           const float la = -c8[tc] * r;
;           const float a = __builtin_amdgcn_exp2f(la);
;           const float ucv = bf2f(sm_uc[(sb * 64 + tl) * LDSS + c]);
;           const float bt = __builtin_amdgcn_sqrtf(fmaxf(1.f - a * a, 0.f)) * (ii * ucv);
;           sm_a[tl * 64 + c] = a;
;           sm_b[tl * 64 + c] = bt;
;     ...
;             const long rowp = row0 + sb * 64 + q * 16 + 15 - i;
;             hfp[i] = hfbuf[rowp * 512 + gch];
;             gp[i] = bf2f(P.zq[rowp * 1536 + 512 + gch]);
;           }
;         }
	v_exp_f32_e32 v20, v20
	v_exp_f32_e32 v21, v21
	v_exp_f32_e32 v22, v22
	v_exp_f32_e32 v23, v23
	s_nop 0
	v_fma_f32 v138, -v20, v20, 1.0
	v_fma_f32 v139, -v21, v21, 1.0
	v_fma_f32 v140, -v22, v22, 1.0
	v_fma_f32 v141, -v23, v23, 1.0
	v_max_f32_e32 v138, 0, v138
	v_max_f32_e32 v139, 0, v139
	v_max_f32_e32 v140, 0, v140
	v_max_f32_e32 v141, 0, v141
	v_sqrt_f32_e32 v138, v138
	v_sqrt_f32_e32 v139, v139
	v_sqrt_f32_e32 v140, v140
	v_sqrt_f32_e32 v141, v141
	s_nop 0
	v_mul_f32_e32 v110, v138, v110
	v_mul_f32_e32 v111, v139, v111
	v_mul_f32_e32 v112, v140, v112
	v_mul_f32_e32 v113, v141, v113
	v_add_f32_e32 v24, v24, v145
	v_add_f32_e32 v25, v25, v145
	v_add_f32_e32 v26, v26, v145
	v_add_f32_e32 v27, v27, v145
	v_add_f32_e32 v114, v114, v146
	v_add_f32_e32 v115, v115, v146
	v_add_f32_e32 v116, v116, v146
	v_add_f32_e32 v117, v117, v146
	v_exp_f32_e32 v24, v24
	v_exp_f32_e32 v25, v25
	v_exp_f32_e32 v26, v26
	v_exp_f32_e32 v27, v27
	v_exp_f32_e32 v114, v114
	v_exp_f32_e32 v115, v115
	v_exp_f32_e32 v116, v116
	v_exp_f32_e32 v117, v117
	v_add_f32_e32 v24, 1.0, v24
	v_add_f32_e32 v25, 1.0, v25
	v_add_f32_e32 v26, 1.0, v26
	v_add_f32_e32 v27, 1.0, v27
	v_add_f32_e32 v114, 1.0, v114
	v_add_f32_e32 v115, 1.0, v115
	v_add_f32_e32 v116, 1.0, v116
	v_add_f32_e32 v117, 1.0, v117
	v_rcp_f32_e32 v24, v24
	v_rcp_f32_e32 v25, v25
	v_rcp_f32_e32 v26, v26
	v_rcp_f32_e32 v27, v27
	v_rcp_f32_e32 v114, v114
	v_rcp_f32_e32 v115, v115
	v_rcp_f32_e32 v116, v116
	v_rcp_f32_e32 v117, v117
	v_mul_f32_e32 v24, v147, v24
	v_mul_f32_e32 v25, v147, v25
	v_mul_f32_e32 v26, v147, v26
	v_mul_f32_e32 v27, v147, v27
	v_mul_f32_e32 v114, v114, v186
	v_mul_f32_e32 v115, v115, v187
	v_mul_f32_e32 v116, v116, v188
	v_mul_f32_e32 v117, v117, v189
	v_exp_f32_e32 v24, v24
	v_exp_f32_e32 v25, v25
	v_exp_f32_e32 v26, v26
	v_exp_f32_e32 v27, v27
	s_nop 0
	v_fma_f32 v138, -v24, v24, 1.0
	v_fma_f32 v139, -v25, v25, 1.0
	v_fma_f32 v140, -v26, v26, 1.0
	v_fma_f32 v141, -v27, v27, 1.0
	v_max_f32_e32 v138, 0, v138
	v_max_f32_e32 v139, 0, v139
	v_max_f32_e32 v140, 0, v140
	v_max_f32_e32 v141, 0, v141
	v_sqrt_f32_e32 v138, v138
	v_sqrt_f32_e32 v139, v139
	v_sqrt_f32_e32 v140, v140
	v_sqrt_f32_e32 v141, v141
	s_nop 0
	v_mul_f32_e32 v114, v138, v114
	v_mul_f32_e32 v115, v139, v115
	v_mul_f32_e32 v116, v140, v116
	v_mul_f32_e32 v117, v141, v117
	v_add_f32_e32 v28, v28, v145
	v_add_f32_e32 v29, v29, v145
	v_add_f32_e32 v30, v30, v145
	v_add_f32_e32 v31, v31, v145
	v_add_f32_e32 v118, v118, v146
	v_add_f32_e32 v119, v119, v146
	v_add_f32_e32 v120, v120, v146
	v_add_f32_e32 v121, v121, v146
	v_exp_f32_e32 v28, v28
	v_exp_f32_e32 v29, v29
	v_exp_f32_e32 v30, v30
	v_exp_f32_e32 v31, v31
	v_exp_f32_e32 v118, v118
	v_exp_f32_e32 v119, v119
	v_exp_f32_e32 v120, v120
	v_exp_f32_e32 v121, v121
	v_add_f32_e32 v28, 1.0, v28
	v_add_f32_e32 v29, 1.0, v29
	v_add_f32_e32 v30, 1.0, v30
	v_add_f32_e32 v31, 1.0, v31
	v_add_f32_e32 v118, 1.0, v118
	v_add_f32_e32 v119, 1.0, v119
	v_add_f32_e32 v120, 1.0, v120
	v_add_f32_e32 v121, 1.0, v121
	v_rcp_f32_e32 v28, v28
	v_rcp_f32_e32 v29, v29
	v_rcp_f32_e32 v30, v30
	v_rcp_f32_e32 v31, v31
	v_rcp_f32_e32 v118, v118
	v_rcp_f32_e32 v119, v119
	v_rcp_f32_e32 v120, v120
	v_rcp_f32_e32 v121, v121
	v_mul_f32_e32 v28, v147, v28
	v_mul_f32_e32 v29, v147, v29
	v_mul_f32_e32 v30, v147, v30
	v_mul_f32_e32 v31, v147, v31
	v_mul_f32_e32 v118, v118, v190
	v_mul_f32_e32 v119, v119, v191
	v_mul_f32_e32 v120, v120, v192
	v_mul_f32_e32 v121, v121, v193
	v_exp_f32_e32 v28, v28
	v_exp_f32_e32 v29, v29
	v_exp_f32_e32 v30, v30
	v_exp_f32_e32 v31, v31
	s_nop 0
	v_fma_f32 v138, -v28, v28, 1.0
	v_fma_f32 v139, -v29, v29, 1.0
	v_fma_f32 v140, -v30, v30, 1.0
	v_fma_f32 v141, -v31, v31, 1.0
	v_max_f32_e32 v138, 0, v138
	v_max_f32_e32 v139, 0, v139
	v_max_f32_e32 v140, 0, v140
	v_max_f32_e32 v141, 0, v141
	v_sqrt_f32_e32 v138, v138
	v_sqrt_f32_e32 v139, v139
	v_sqrt_f32_e32 v140, v140
	v_sqrt_f32_e32 v141, v141
	s_nop 0
	v_mul_f32_e32 v118, v138, v118
	v_mul_f32_e32 v119, v139, v119
	v_mul_f32_e32 v120, v140, v120
	v_mul_f32_e32 v121, v141, v121
	s_and_b32 s0, s69, 1
	s_mul_i32 s0, s0, 0x4100
	v_add_u32_e32 v137, s0, v132
	ds_read_u16 v162, v137 offset:0
	ds_read_u16 v163, v137 offset:128
	ds_read_u16 v164, v137 offset:256
	ds_read_u16 v165, v137 offset:384
	ds_read_u16 v166, v137 offset:512
	ds_read_u16 v167, v137 offset:640
	ds_read_u16 v168, v137 offset:768
	ds_read_u16 v169, v137 offset:896
	ds_read_u16 v170, v137 offset:1024
	ds_read_u16 v171, v137 offset:1152
	ds_read_u16 v172, v137 offset:1280
	ds_read_u16 v173, v137 offset:1408
	ds_read_u16 v174, v137 offset:1536
	ds_read_u16 v175, v137 offset:1664
	ds_read_u16 v176, v137 offset:1792
	ds_read_u16 v177, v137 offset:1920
	ds_read_u16 v178, v137 offset:2048
	ds_read_u16 v179, v137 offset:2176
	ds_read_u16 v180, v137 offset:2304
	ds_read_u16 v181, v137 offset:2432
	ds_read_u16 v182, v137 offset:2560
	ds_read_u16 v183, v137 offset:2688
	ds_read_u16 v184, v137 offset:2816
	ds_read_u16 v185, v137 offset:2944
	ds_read_u16 v186, v137 offset:3072
	ds_read_u16 v187, v137 offset:3200
	ds_read_u16 v188, v137 offset:3328
	ds_read_u16 v189, v137 offset:3456
	ds_read_u16 v190, v137 offset:3584
	ds_read_u16 v191, v137 offset:3712
	ds_read_u16 v192, v137 offset:3840
	ds_read_u16 v193, v137 offset:3968
	v_mov_b32_e32 v253, v31
	v_mov_b32_e32 v254, v121
	v_fma_f32 v254, v30, v254, v120
	v_mul_f32_e32 v253, v253, v30
	v_fma_f32 v254, v29, v254, v119
	v_mul_f32_e32 v253, v253, v29
	v_fma_f32 v254, v28, v254, v118
	v_mul_f32_e32 v253, v253, v28
	v_fma_f32 v254, v27, v254, v117
	v_mul_f32_e32 v253, v253, v27
	v_fma_f32 v254, v26, v254, v116
	v_mul_f32_e32 v253, v253, v26
; __device__ __forceinline__ float bf2f(u16 h) { return __uint_as_float(((unsigned)h) << 16); }
; __device__ __forceinline__ void lru_tile(const Params& P, int chunk, int head, int pass, char* smem_raw) {
;     ...
;       const float2 p0 = sm_ph[ch], p1 = sm_ph[64 + ch], p2 = sm_ph[128 + ch], p3 = sm_ph[192 + ch];
;       if (pass == 2) {
;         float hin = cB;
;         if (pos > 0) hin = p0.x * hin + p0.y;
;         if (pos > 1) hin = p1.x * hin + p1.y;
;         if (pos > 2) hin = p2.x * hin + p2.y;
;         float h = hin;
;         float hfp[16], gp[16];
;         if (d == 1) {
; #pragma unroll
;           for (int i = 0; i < 16; ++i) {
;             const long rowp = row0 + sb * 64 + q * 16 + 15 - i;
;             hfp[i] = hfbuf[rowp * 512 + gch];
;             gp[i] = bf2f(P.zq[rowp * 1536 + 512 + gch]);
;           }
;         }
; #pragma unroll
;         for (int i = 0; i < 16; ++i) {
;           const int tl = (d == 0) ? (q * 16 + i) : (q * 16 + 15 - i);
;           const float a = sm_a[tl * 64 + ch], b = sm_b[tl * 64 + ch];
;           h = a * h + b;
;           const long row = row0 + sb * 64 + tl;
;           if (d == 0) {
;             hfw[row * 512 + gch] = h;
;           } else {
;             const float hfv = hfp[i];
;             const float g = gp[i];
;             const float tz = 0.7978845608028654f * (g + 0.044715f * g * g * g);
;             const float th = 1.f - 2.f * __builtin_amdgcn_rcpf(1.f + __expf(2.f * tz));
;             const float ge = 0.5f * g * (1.f + th);
	v_fma_f32 v254, v25, v254, v115
	v_mul_f32_e32 v253, v253, v25
	v_fma_f32 v254, v24, v254, v114
	v_mul_f32_e32 v253, v253, v24
	v_fma_f32 v254, v23, v254, v113
	v_mul_f32_e32 v253, v253, v23
	v_fma_f32 v254, v22, v254, v112
	v_mul_f32_e32 v253, v253, v22
	v_fma_f32 v254, v21, v254, v111
	v_mul_f32_e32 v253, v253, v21
	v_fma_f32 v254, v20, v254, v110
	v_mul_f32_e32 v253, v253, v20
	v_fma_f32 v254, v19, v254, v109
	v_mul_f32_e32 v253, v253, v19
	v_fma_f32 v254, v18, v254, v108
	v_mul_f32_e32 v253, v253, v18
	v_fma_f32 v254, v17, v254, v107
	v_mul_f32_e32 v253, v253, v17
	v_fma_f32 v254, v16, v254, v106
	v_mul_f32_e32 v253, v253, v16
	v_fma_f32 v254, v15, v254, v105
	v_mul_f32_e32 v253, v253, v15
	v_fma_f32 v254, v14, v254, v104
	v_mul_f32_e32 v253, v253, v14
	v_fma_f32 v254, v13, v254, v103
	v_mul_f32_e32 v253, v253, v13
	v_fma_f32 v254, v12, v254, v102
	v_mul_f32_e32 v253, v253, v12
	v_fma_f32 v254, v11, v254, v101
	v_mul_f32_e32 v253, v253, v11
	v_fma_f32 v254, v10, v254, v100
	v_mul_f32_e32 v253, v253, v10
	v_fma_f32 v254, v9, v254, v99
	v_mul_f32_e32 v253, v253, v9
	v_fma_f32 v254, v8, v254, v98
	v_mul_f32_e32 v253, v253, v8
	v_fma_f32 v254, v7, v254, v97
	v_mul_f32_e32 v253, v253, v7
	v_fma_f32 v254, v6, v254, v96
	v_mul_f32_e32 v253, v253, v6
	v_fma_f32 v254, v5, v254, v95
	v_mul_f32_e32 v253, v253, v5
	v_fma_f32 v254, v4, v254, v94
	v_mul_f32_e32 v253, v253, v4
	v_fma_f32 v254, v3, v254, v93
	v_mul_f32_e32 v253, v253, v3
	v_fma_f32 v254, v2, v254, v92
	v_mul_f32_e32 v253, v253, v2
	v_fma_f32 v254, v1, v254, v91
	v_mul_f32_e32 v253, v253, v1
	v_fma_f32 v254, v0, v254, v90
	v_mul_f32_e32 v253, v253, v0
	v_mov_b32_e32 v138, v253
	v_mov_b32_e32 v139, v253
	s_nop 1
	v_permlane16_swap_b32_e32 v138, v139
	v_mov_b32_e32 v140, v138
	v_mov_b32_e32 v141, v139
	s_nop 1
	v_permlane32_swap_b32_e32 v138, v140
	v_permlane32_swap_b32_e32 v139, v141
	v_mov_b32_e32 v198, v254
	v_mov_b32_e32 v199, v254
	s_nop 1
	v_permlane16_swap_b32_e32 v198, v199
	v_mov_b32_e32 v200, v198
	v_mov_b32_e32 v201, v199
	s_nop 1
	v_permlane32_swap_b32_e32 v198, v200
	v_permlane32_swap_b32_e32 v199, v201
	v_mov_b32_e32 v202, v149
	v_fma_f32 v151, v141, v202, v201
	v_fma_f32 v150, v140, v151, v200
	v_fma_f32 v136, v139, v150, v199
	v_mov_b32_e32 v254, v202
	v_cndmask_b32_e64 v254, v254, v151, s[78:79]
	v_cndmask_b32_e64 v254, v254, v150, s[80:81]
	v_cndmask_b32_e64 v254, v254, v136, s[82:83]
	v_fma_f32 v121, v31, v254, v121
	v_fma_f32 v120, v30, v121, v120
	v_fma_f32 v119, v29, v120, v119
	v_fma_f32 v118, v28, v119, v118
	v_fma_f32 v117, v27, v118, v117
	v_fma_f32 v116, v26, v117, v116
	v_fma_f32 v115, v25, v116, v115
	v_fma_f32 v114, v24, v115, v114
	v_fma_f32 v113, v23, v114, v113
	v_fma_f32 v112, v22, v113, v112
	v_fma_f32 v111, v21, v112, v111
	v_fma_f32 v110, v20, v111, v110
	v_fma_f32 v109, v19, v110, v109
	v_fma_f32 v108, v18, v109, v108
	v_fma_f32 v107, v17, v108, v107
	v_fma_f32 v106, v16, v107, v106
	v_fma_f32 v105, v15, v106, v105
	v_fma_f32 v104, v14, v105, v104
	v_fma_f32 v103, v13, v104, v103
	v_fma_f32 v102, v12, v103, v102
	v_fma_f32 v101, v11, v102, v101
	v_fma_f32 v100, v10, v101, v100
	v_fma_f32 v99, v9, v100, v99
	v_fma_f32 v98, v8, v99, v98
	v_fma_f32 v97, v7, v98, v97
	v_fma_f32 v96, v6, v97, v96
	v_fma_f32 v95, v5, v96, v95
	v_fma_f32 v94, v4, v95, v94
	v_fma_f32 v93, v3, v94, v93
	v_fma_f32 v92, v2, v93, v92
	v_fma_f32 v91, v1, v92, v91
	v_fma_f32 v90, v0, v91, v90
	s_waitcnt lgkmcnt(0)
	v_lshlrev_b32_e32 v162, 16, v162
	v_lshlrev_b32_e32 v163, 16, v163
	v_lshlrev_b32_e32 v164, 16, v164
	v_lshlrev_b32_e32 v165, 16, v165
	v_lshlrev_b32_e32 v166, 16, v166
	v_lshlrev_b32_e32 v167, 16, v167
	v_lshlrev_b32_e32 v168, 16, v168
	v_lshlrev_b32_e32 v169, 16, v169
	v_lshlrev_b32_e32 v170, 16, v170
	v_lshlrev_b32_e32 v171, 16, v171
	v_lshlrev_b32_e32 v172, 16, v172
	v_lshlrev_b32_e32 v173, 16, v173
	v_lshlrev_b32_e32 v174, 16, v174
	v_lshlrev_b32_e32 v175, 16, v175
	v_lshlrev_b32_e32 v176, 16, v176
	v_lshlrev_b32_e32 v177, 16, v177
	v_lshlrev_b32_e32 v178, 16, v178
	v_lshlrev_b32_e32 v179, 16, v179
	v_lshlrev_b32_e32 v180, 16, v180
	v_lshlrev_b32_e32 v181, 16, v181
	v_lshlrev_b32_e32 v182, 16, v182
	v_lshlrev_b32_e32 v183, 16, v183
	v_lshlrev_b32_e32 v184, 16, v184
	v_lshlrev_b32_e32 v185, 16, v185
	v_lshlrev_b32_e32 v186, 16, v186
	v_lshlrev_b32_e32 v187, 16, v187
	v_lshlrev_b32_e32 v188, 16, v188
	v_lshlrev_b32_e32 v189, 16, v189
	v_lshlrev_b32_e32 v190, 16, v190
	v_lshlrev_b32_e32 v191, 16, v191
	v_lshlrev_b32_e32 v192, 16, v192
	v_lshlrev_b32_e32 v193, 16, v193
	v_mov_b32_e32 v202, 0x3d372713
	v_mul_f32_e32 v138, v162, v162
	v_mul_f32_e32 v139, v163, v163
	v_mul_f32_e32 v140, v164, v164
	v_mul_f32_e32 v141, v165, v165
	v_mul_f32_e32 v138, v138, v162
	v_mul_f32_e32 v139, v139, v163
	v_mul_f32_e32 v140, v140, v164
	v_mul_f32_e32 v141, v141, v165
	v_fma_f32 v138, v202, v138, v162
	v_fma_f32 v139, v202, v139, v163
	v_fma_f32 v140, v202, v140, v164
	v_fma_f32 v141, v202, v141, v165
	v_mul_f32_e32 v138, 0x40135761, v138
	v_mul_f32_e32 v139, 0x40135761, v139
	v_mul_f32_e32 v140, 0x40135761, v140
	v_mul_f32_e32 v141, 0x40135761, v141
	v_exp_f32_e32 v138, v138
	v_exp_f32_e32 v139, v139
	v_exp_f32_e32 v140, v140
	v_exp_f32_e32 v141, v141
	s_nop 0
	v_add_f32_e32 v138, 1.0, v138
	v_add_f32_e32 v139, 1.0, v139
	v_add_f32_e32 v140, 1.0, v140
	v_add_f32_e32 v141, 1.0, v141
	v_rcp_f32_e32 v138, v138
	v_rcp_f32_e32 v139, v139
	v_rcp_f32_e32 v140, v140
	v_rcp_f32_e32 v141, v141
	s_nop 0
	v_fma_f32 v138, -2.0, v138, 1.0
	v_fma_f32 v139, -2.0, v139, 1.0
	v_fma_f32 v140, -2.0, v140, 1.0
	v_fma_f32 v141, -2.0, v141, 1.0
	v_add_f32_e32 v138, 1.0, v138
	v_add_f32_e32 v139, 1.0, v139
; __device__ __forceinline__ void lru_tile(const Params& P, int chunk, int head, int pass, char* smem_raw) {
;     ...
;             const float hfv = hfp[i];
;             const float g = gp[i];
;             const float tz = 0.7978845608028654f * (g + 0.044715f * g * g * g);
;             const float th = 1.f - 2.f * __builtin_amdgcn_rcpf(1.f + __expf(2.f * tz));
;             const float ge = 0.5f * g * (1.f + th);
;             P.cat[row * 1024 + gch] = f2bf((hfv + h) * ge);
	v_add_f32_e32 v140, 1.0, v140
	v_add_f32_e32 v141, 1.0, v141
	v_mul_f32_e32 v162, 0.5, v162
	v_mul_f32_e32 v163, 0.5, v163
	v_mul_f32_e32 v164, 0.5, v164
	v_mul_f32_e32 v165, 0.5, v165
	v_mul_f32_e32 v162, v162, v138
	v_mul_f32_e32 v163, v163, v139
	v_mul_f32_e32 v164, v164, v140
	v_mul_f32_e32 v165, v165, v141
	v_add_f32_e32 v90, v205, v90
	v_add_f32_e32 v91, v206, v91
	v_add_f32_e32 v92, v207, v92
	v_add_f32_e32 v93, v208, v93
	v_mul_f32_e32 v90, v90, v162
	v_mul_f32_e32 v91, v91, v163
	v_mul_f32_e32 v92, v92, v164
	v_mul_f32_e32 v93, v93, v165
	v_cvt_pk_bf16_f32 v90, v90, v90
	v_cvt_pk_bf16_f32 v91, v91, v91
	v_cvt_pk_bf16_f32 v92, v92, v92
	v_cvt_pk_bf16_f32 v93, v93, v93
	v_mul_f32_e32 v138, v166, v166
	v_mul_f32_e32 v139, v167, v167
	v_mul_f32_e32 v140, v168, v168
	v_mul_f32_e32 v141, v169, v169
	v_mul_f32_e32 v138, v138, v166
	v_mul_f32_e32 v139, v139, v167
	v_mul_f32_e32 v140, v140, v168
	v_mul_f32_e32 v141, v141, v169
	v_fma_f32 v138, v202, v138, v166
	v_fma_f32 v139, v202, v139, v167
	v_fma_f32 v140, v202, v140, v168
	v_fma_f32 v141, v202, v141, v169
	v_mul_f32_e32 v138, 0x40135761, v138
	v_mul_f32_e32 v139, 0x40135761, v139
	v_mul_f32_e32 v140, 0x40135761, v140
	v_mul_f32_e32 v141, 0x40135761, v141
	v_exp_f32_e32 v138, v138
	v_exp_f32_e32 v139, v139
	v_exp_f32_e32 v140, v140
	v_exp_f32_e32 v141, v141
	s_nop 0
	v_add_f32_e32 v138, 1.0, v138
	v_add_f32_e32 v139, 1.0, v139
	v_add_f32_e32 v140, 1.0, v140
	v_add_f32_e32 v141, 1.0, v141
	v_rcp_f32_e32 v138, v138
	v_rcp_f32_e32 v139, v139
	v_rcp_f32_e32 v140, v140
	v_rcp_f32_e32 v141, v141
	s_nop 0
	v_fma_f32 v138, -2.0, v138, 1.0
	v_fma_f32 v139, -2.0, v139, 1.0
	v_fma_f32 v140, -2.0, v140, 1.0
	v_fma_f32 v141, -2.0, v141, 1.0
	v_add_f32_e32 v138, 1.0, v138
	v_add_f32_e32 v139, 1.0, v139
	v_add_f32_e32 v140, 1.0, v140
	v_add_f32_e32 v141, 1.0, v141
	v_mul_f32_e32 v166, 0.5, v166
	v_mul_f32_e32 v167, 0.5, v167
	v_mul_f32_e32 v168, 0.5, v168
	v_mul_f32_e32 v169, 0.5, v169
	v_mul_f32_e32 v166, v166, v138
	v_mul_f32_e32 v167, v167, v139
	v_mul_f32_e32 v168, v168, v140
	v_mul_f32_e32 v169, v169, v141
	v_add_f32_e32 v94, v209, v94
	v_add_f32_e32 v95, v210, v95
	v_add_f32_e32 v96, v211, v96
	v_add_f32_e32 v97, v212, v97
	v_mul_f32_e32 v94, v94, v166
	v_mul_f32_e32 v95, v95, v167
	v_mul_f32_e32 v96, v96, v168
	v_mul_f32_e32 v97, v97, v169
	v_cvt_pk_bf16_f32 v94, v94, v94
	v_cvt_pk_bf16_f32 v95, v95, v95
	v_cvt_pk_bf16_f32 v96, v96, v96
	v_cvt_pk_bf16_f32 v97, v97, v97
	v_mul_f32_e32 v138, v170, v170
	v_mul_f32_e32 v139, v171, v171
	v_mul_f32_e32 v140, v172, v172
	v_mul_f32_e32 v141, v173, v173
	v_mul_f32_e32 v138, v138, v170
	v_mul_f32_e32 v139, v139, v171
	v_mul_f32_e32 v140, v140, v172
	v_mul_f32_e32 v141, v141, v173
	v_fma_f32 v138, v202, v138, v170
	v_fma_f32 v139, v202, v139, v171
	v_fma_f32 v140, v202, v140, v172
	v_fma_f32 v141, v202, v141, v173
	v_mul_f32_e32 v138, 0x40135761, v138
	v_mul_f32_e32 v139, 0x40135761, v139
	v_mul_f32_e32 v140, 0x40135761, v140
	v_mul_f32_e32 v141, 0x40135761, v141
	v_exp_f32_e32 v138, v138
	v_exp_f32_e32 v139, v139
	v_exp_f32_e32 v140, v140
	v_exp_f32_e32 v141, v141
	s_nop 0
	v_add_f32_e32 v138, 1.0, v138
	v_add_f32_e32 v139, 1.0, v139
	v_add_f32_e32 v140, 1.0, v140
	v_add_f32_e32 v141, 1.0, v141
	v_rcp_f32_e32 v138, v138
	v_rcp_f32_e32 v139, v139
	v_rcp_f32_e32 v140, v140
	v_rcp_f32_e32 v141, v141
	s_nop 0
	v_fma_f32 v138, -2.0, v138, 1.0
	v_fma_f32 v139, -2.0, v139, 1.0
	v_fma_f32 v140, -2.0, v140, 1.0
	v_fma_f32 v141, -2.0, v141, 1.0
	v_add_f32_e32 v138, 1.0, v138
	v_add_f32_e32 v139, 1.0, v139
	v_add_f32_e32 v140, 1.0, v140
	v_add_f32_e32 v141, 1.0, v141
	v_mul_f32_e32 v170, 0.5, v170
	v_mul_f32_e32 v171, 0.5, v171
	v_mul_f32_e32 v172, 0.5, v172
	v_mul_f32_e32 v173, 0.5, v173
	v_mul_f32_e32 v170, v170, v138
	v_mul_f32_e32 v171, v171, v139
	v_mul_f32_e32 v172, v172, v140
	v_mul_f32_e32 v173, v173, v141
	v_add_f32_e32 v98, v213, v98
	v_add_f32_e32 v99, v214, v99
	v_add_f32_e32 v100, v215, v100
	v_add_f32_e32 v101, v216, v101
	v_mul_f32_e32 v98, v98, v170
	v_mul_f32_e32 v99, v99, v171
	v_mul_f32_e32 v100, v100, v172
	v_mul_f32_e32 v101, v101, v173
	v_cvt_pk_bf16_f32 v98, v98, v98
	v_cvt_pk_bf16_f32 v99, v99, v99
	v_cvt_pk_bf16_f32 v100, v100, v100
	v_cvt_pk_bf16_f32 v101, v101, v101
	v_mul_f32_e32 v138, v174, v174
	v_mul_f32_e32 v139, v175, v175
	v_mul_f32_e32 v140, v176, v176
	v_mul_f32_e32 v141, v177, v177
	v_mul_f32_e32 v138, v138, v174
	v_mul_f32_e32 v139, v139, v175
	v_mul_f32_e32 v140, v140, v176
	v_mul_f32_e32 v141, v141, v177
	v_fma_f32 v138, v202, v138, v174
	v_fma_f32 v139, v202, v139, v175
	v_fma_f32 v140, v202, v140, v176
	v_fma_f32 v141, v202, v141, v177
	v_mul_f32_e32 v138, 0x40135761, v138
	v_mul_f32_e32 v139, 0x40135761, v139
	v_mul_f32_e32 v140, 0x40135761, v140
	v_mul_f32_e32 v141, 0x40135761, v141
	v_exp_f32_e32 v138, v138
	v_exp_f32_e32 v139, v139
	v_exp_f32_e32 v140, v140
	v_exp_f32_e32 v141, v141
	s_nop 0
	v_add_f32_e32 v138, 1.0, v138
	v_add_f32_e32 v139, 1.0, v139
	v_add_f32_e32 v140, 1.0, v140
	v_add_f32_e32 v141, 1.0, v141
	v_rcp_f32_e32 v138, v138
	v_rcp_f32_e32 v139, v139
	v_rcp_f32_e32 v140, v140
	v_rcp_f32_e32 v141, v141
	s_nop 0
	v_fma_f32 v138, -2.0, v138, 1.0
	v_fma_f32 v139, -2.0, v139, 1.0
	v_fma_f32 v140, -2.0, v140, 1.0
	v_fma_f32 v141, -2.0, v141, 1.0
	v_add_f32_e32 v138, 1.0, v138
	v_add_f32_e32 v139, 1.0, v139
	v_add_f32_e32 v140, 1.0, v140
	v_add_f32_e32 v141, 1.0, v141
	v_mul_f32_e32 v174, 0.5, v174
	v_mul_f32_e32 v175, 0.5, v175
	v_mul_f32_e32 v176, 0.5, v176
	v_mul_f32_e32 v177, 0.5, v177
	v_mul_f32_e32 v174, v174, v138
	v_mul_f32_e32 v175, v175, v139
	v_mul_f32_e32 v176, v176, v140
	v_mul_f32_e32 v177, v177, v141
; __device__ __forceinline__ void lru_tile(const Params& P, int chunk, int head, int pass, char* smem_raw) {
;     ...
;             const float hfv = hfp[i];
;             const float g = gp[i];
;             const float tz = 0.7978845608028654f * (g + 0.044715f * g * g * g);
;             const float th = 1.f - 2.f * __builtin_amdgcn_rcpf(1.f + __expf(2.f * tz));
;             const float ge = 0.5f * g * (1.f + th);
;             P.cat[row * 1024 + gch] = f2bf((hfv + h) * ge);
	v_add_f32_e32 v102, v217, v102
	v_add_f32_e32 v103, v218, v103
	v_add_f32_e32 v104, v219, v104
	v_add_f32_e32 v105, v220, v105
	v_mul_f32_e32 v102, v102, v174
	v_mul_f32_e32 v103, v103, v175
	v_mul_f32_e32 v104, v104, v176
	v_mul_f32_e32 v105, v105, v177
	v_cvt_pk_bf16_f32 v102, v102, v102
	v_cvt_pk_bf16_f32 v103, v103, v103
	v_cvt_pk_bf16_f32 v104, v104, v104
	v_cvt_pk_bf16_f32 v105, v105, v105
	v_mul_f32_e32 v138, v178, v178
	v_mul_f32_e32 v139, v179, v179
	v_mul_f32_e32 v140, v180, v180
	v_mul_f32_e32 v141, v181, v181
	v_mul_f32_e32 v138, v138, v178
	v_mul_f32_e32 v139, v139, v179
	v_mul_f32_e32 v140, v140, v180
	v_mul_f32_e32 v141, v141, v181
	v_fma_f32 v138, v202, v138, v178
	v_fma_f32 v139, v202, v139, v179
	v_fma_f32 v140, v202, v140, v180
	v_fma_f32 v141, v202, v141, v181
	v_mul_f32_e32 v138, 0x40135761, v138
	v_mul_f32_e32 v139, 0x40135761, v139
	v_mul_f32_e32 v140, 0x40135761, v140
	v_mul_f32_e32 v141, 0x40135761, v141
	v_exp_f32_e32 v138, v138
	v_exp_f32_e32 v139, v139
	v_exp_f32_e32 v140, v140
	v_exp_f32_e32 v141, v141
	s_nop 0
	v_add_f32_e32 v138, 1.0, v138
	v_add_f32_e32 v139, 1.0, v139
	v_add_f32_e32 v140, 1.0, v140
	v_add_f32_e32 v141, 1.0, v141
	v_rcp_f32_e32 v138, v138
	v_rcp_f32_e32 v139, v139
	v_rcp_f32_e32 v140, v140
	v_rcp_f32_e32 v141, v141
	s_nop 0
	v_fma_f32 v138, -2.0, v138, 1.0
	v_fma_f32 v139, -2.0, v139, 1.0
	v_fma_f32 v140, -2.0, v140, 1.0
	v_fma_f32 v141, -2.0, v141, 1.0
	v_add_f32_e32 v138, 1.0, v138
	v_add_f32_e32 v139, 1.0, v139
	v_add_f32_e32 v140, 1.0, v140
	v_add_f32_e32 v141, 1.0, v141
	v_mul_f32_e32 v178, 0.5, v178
	v_mul_f32_e32 v179, 0.5, v179
	v_mul_f32_e32 v180, 0.5, v180
	v_mul_f32_e32 v181, 0.5, v181
	v_mul_f32_e32 v178, v178, v138
	v_mul_f32_e32 v179, v179, v139
	v_mul_f32_e32 v180, v180, v140
	v_mul_f32_e32 v181, v181, v141
	v_add_f32_e32 v106, v221, v106
	v_add_f32_e32 v107, v222, v107
	v_add_f32_e32 v108, v223, v108
	v_add_f32_e32 v109, v224, v109
	v_mul_f32_e32 v106, v106, v178
	v_mul_f32_e32 v107, v107, v179
	v_mul_f32_e32 v108, v108, v180
	v_mul_f32_e32 v109, v109, v181
	v_cvt_pk_bf16_f32 v106, v106, v106
	v_cvt_pk_bf16_f32 v107, v107, v107
	v_cvt_pk_bf16_f32 v108, v108, v108
	v_cvt_pk_bf16_f32 v109, v109, v109
	v_mul_f32_e32 v138, v182, v182
	v_mul_f32_e32 v139, v183, v183
	v_mul_f32_e32 v140, v184, v184
	v_mul_f32_e32 v141, v185, v185
	v_mul_f32_e32 v138, v138, v182
	v_mul_f32_e32 v139, v139, v183
	v_mul_f32_e32 v140, v140, v184
	v_mul_f32_e32 v141, v141, v185
	v_fma_f32 v138, v202, v138, v182
	v_fma_f32 v139, v202, v139, v183
	v_fma_f32 v140, v202, v140, v184
	v_fma_f32 v141, v202, v141, v185
	v_mul_f32_e32 v138, 0x40135761, v138
	v_mul_f32_e32 v139, 0x40135761, v139
	v_mul_f32_e32 v140, 0x40135761, v140
	v_mul_f32_e32 v141, 0x40135761, v141
	v_exp_f32_e32 v138, v138
	v_exp_f32_e32 v139, v139
	v_exp_f32_e32 v140, v140
	v_exp_f32_e32 v141, v141
	s_nop 0
	v_add_f32_e32 v138, 1.0, v138
	v_add_f32_e32 v139, 1.0, v139
	v_add_f32_e32 v140, 1.0, v140
	v_add_f32_e32 v141, 1.0, v141
	v_rcp_f32_e32 v138, v138
	v_rcp_f32_e32 v139, v139
	v_rcp_f32_e32 v140, v140
	v_rcp_f32_e32 v141, v141
	s_nop 0
	v_fma_f32 v138, -2.0, v138, 1.0
	v_fma_f32 v139, -2.0, v139, 1.0
	v_fma_f32 v140, -2.0, v140, 1.0
	v_fma_f32 v141, -2.0, v141, 1.0
	v_add_f32_e32 v138, 1.0, v138
	v_add_f32_e32 v139, 1.0, v139
	v_add_f32_e32 v140, 1.0, v140
	v_add_f32_e32 v141, 1.0, v141
	v_mul_f32_e32 v182, 0.5, v182
	v_mul_f32_e32 v183, 0.5, v183
	v_mul_f32_e32 v184, 0.5, v184
	v_mul_f32_e32 v185, 0.5, v185
	v_mul_f32_e32 v182, v182, v138
	v_mul_f32_e32 v183, v183, v139
	v_mul_f32_e32 v184, v184, v140
	v_mul_f32_e32 v185, v185, v141
	v_add_f32_e32 v110, v225, v110
	v_add_f32_e32 v111, v226, v111
	v_add_f32_e32 v112, v227, v112
	v_add_f32_e32 v113, v228, v113
	v_mul_f32_e32 v110, v110, v182
	v_mul_f32_e32 v111, v111, v183
	v_mul_f32_e32 v112, v112, v184
	v_mul_f32_e32 v113, v113, v185
	v_cvt_pk_bf16_f32 v110, v110, v110
	v_cvt_pk_bf16_f32 v111, v111, v111
	v_cvt_pk_bf16_f32 v112, v112, v112
	v_cvt_pk_bf16_f32 v113, v113, v113
	v_mul_f32_e32 v138, v186, v186
	v_mul_f32_e32 v139, v187, v187
	v_mul_f32_e32 v140, v188, v188
	v_mul_f32_e32 v141, v189, v189
	v_mul_f32_e32 v138, v138, v186
	v_mul_f32_e32 v139, v139, v187
	v_mul_f32_e32 v140, v140, v188
	v_mul_f32_e32 v141, v141, v189
	v_fma_f32 v138, v202, v138, v186
	v_fma_f32 v139, v202, v139, v187
	v_fma_f32 v140, v202, v140, v188
	v_fma_f32 v141, v202, v141, v189
	v_mul_f32_e32 v138, 0x40135761, v138
	v_mul_f32_e32 v139, 0x40135761, v139
	v_mul_f32_e32 v140, 0x40135761, v140
	v_mul_f32_e32 v141, 0x40135761, v141
	v_exp_f32_e32 v138, v138
	v_exp_f32_e32 v139, v139
	v_exp_f32_e32 v140, v140
	v_exp_f32_e32 v141, v141
	s_nop 0
	v_add_f32_e32 v138, 1.0, v138
	v_add_f32_e32 v139, 1.0, v139
	v_add_f32_e32 v140, 1.0, v140
	v_add_f32_e32 v141, 1.0, v141
	v_rcp_f32_e32 v138, v138
	v_rcp_f32_e32 v139, v139
	v_rcp_f32_e32 v140, v140
	v_rcp_f32_e32 v141, v141
	s_nop 0
	v_fma_f32 v138, -2.0, v138, 1.0
	v_fma_f32 v139, -2.0, v139, 1.0
	v_fma_f32 v140, -2.0, v140, 1.0
	v_fma_f32 v141, -2.0, v141, 1.0
	v_add_f32_e32 v138, 1.0, v138
	v_add_f32_e32 v139, 1.0, v139
	v_add_f32_e32 v140, 1.0, v140
	v_add_f32_e32 v141, 1.0, v141
	v_mul_f32_e32 v186, 0.5, v186
	v_mul_f32_e32 v187, 0.5, v187
	v_mul_f32_e32 v188, 0.5, v188
	v_mul_f32_e32 v189, 0.5, v189
; __device__ __forceinline__ void lru_tile(const Params& P, int chunk, int head, int pass, char* smem_raw) {
;     ...
;             const float hfv = hfp[i];
;             const float g = gp[i];
;             const float tz = 0.7978845608028654f * (g + 0.044715f * g * g * g);
;             const float th = 1.f - 2.f * __builtin_amdgcn_rcpf(1.f + __expf(2.f * tz));
;             const float ge = 0.5f * g * (1.f + th);
;             P.cat[row * 1024 + gch] = f2bf((hfv + h) * ge);
; __device__ __forceinline__ void run_phase(const Params& P, const int ph, char* smem_raw) {
;     ...
;       for (int t = VBID; t < 2112; t += VGRID) lru_tile(P, t >> 3, t & 7, 2, smv_raw);
	v_mul_f32_e32 v186, v186, v138
	v_mul_f32_e32 v187, v187, v139
	v_mul_f32_e32 v188, v188, v140
	v_mul_f32_e32 v189, v189, v141
	v_add_f32_e32 v114, v229, v114
	v_add_f32_e32 v115, v230, v115
	v_add_f32_e32 v116, v231, v116
	v_add_f32_e32 v117, v232, v117
	v_mul_f32_e32 v114, v114, v186
	v_mul_f32_e32 v115, v115, v187
	v_mul_f32_e32 v116, v116, v188
	v_mul_f32_e32 v117, v117, v189
	v_cvt_pk_bf16_f32 v114, v114, v114
	v_cvt_pk_bf16_f32 v115, v115, v115
	v_cvt_pk_bf16_f32 v116, v116, v116
	v_cvt_pk_bf16_f32 v117, v117, v117
	v_mul_f32_e32 v138, v190, v190
	v_mul_f32_e32 v139, v191, v191
	v_mul_f32_e32 v140, v192, v192
	v_mul_f32_e32 v141, v193, v193
	v_mul_f32_e32 v138, v138, v190
	v_mul_f32_e32 v139, v139, v191
	v_mul_f32_e32 v140, v140, v192
	v_mul_f32_e32 v141, v141, v193
	v_fma_f32 v138, v202, v138, v190
	v_fma_f32 v139, v202, v139, v191
	v_fma_f32 v140, v202, v140, v192
	v_fma_f32 v141, v202, v141, v193
	v_mul_f32_e32 v138, 0x40135761, v138
	v_mul_f32_e32 v139, 0x40135761, v139
	v_mul_f32_e32 v140, 0x40135761, v140
	v_mul_f32_e32 v141, 0x40135761, v141
	v_exp_f32_e32 v138, v138
	v_exp_f32_e32 v139, v139
	v_exp_f32_e32 v140, v140
	v_exp_f32_e32 v141, v141
	s_nop 0
	v_add_f32_e32 v138, 1.0, v138
	v_add_f32_e32 v139, 1.0, v139
	v_add_f32_e32 v140, 1.0, v140
	v_add_f32_e32 v141, 1.0, v141
	v_rcp_f32_e32 v138, v138
	v_rcp_f32_e32 v139, v139
	v_rcp_f32_e32 v140, v140
	v_rcp_f32_e32 v141, v141
	s_nop 0
	v_fma_f32 v138, -2.0, v138, 1.0
	v_fma_f32 v139, -2.0, v139, 1.0
	v_fma_f32 v140, -2.0, v140, 1.0
	v_fma_f32 v141, -2.0, v141, 1.0
	v_add_f32_e32 v138, 1.0, v138
	v_add_f32_e32 v139, 1.0, v139
	v_add_f32_e32 v140, 1.0, v140
	v_add_f32_e32 v141, 1.0, v141
	v_mul_f32_e32 v190, 0.5, v190
	v_mul_f32_e32 v191, 0.5, v191
	v_mul_f32_e32 v192, 0.5, v192
	v_mul_f32_e32 v193, 0.5, v193
	v_mul_f32_e32 v190, v190, v138
	v_mul_f32_e32 v191, v191, v139
	v_mul_f32_e32 v192, v192, v140
	v_mul_f32_e32 v193, v193, v141
	v_add_f32_e32 v118, v233, v118
	v_add_f32_e32 v119, v234, v119
	v_add_f32_e32 v120, v235, v120
	v_add_f32_e32 v121, v236, v121
	v_mul_f32_e32 v118, v118, v190
	v_mul_f32_e32 v119, v119, v191
	v_mul_f32_e32 v120, v120, v192
	v_mul_f32_e32 v121, v121, v193
	v_cvt_pk_bf16_f32 v118, v118, v118
	v_cvt_pk_bf16_f32 v119, v119, v119
	v_cvt_pk_bf16_f32 v120, v120, v120
	v_cvt_pk_bf16_f32 v121, v121, v121
	s_lshl_b32 s0, s71, 18
	s_lshl_b32 s1, s56, 1
	s_add_u32 s0, s0, s1
	s_add_u32 s4, s12, s0
	s_addc_u32 s5, s13, 0
	global_store_short v237, v90, s[4:5]
	s_add_u32 s4, s4, 0x800
	s_addc_u32 s5, s5, 0
	global_store_short v237, v91, s[4:5]
	s_add_u32 s4, s4, 0x800
	s_addc_u32 s5, s5, 0
	global_store_short v237, v92, s[4:5]
	s_add_u32 s4, s4, 0x800
	s_addc_u32 s5, s5, 0
	global_store_short v237, v93, s[4:5]
	s_add_u32 s4, s4, 0x800
	s_addc_u32 s5, s5, 0
	global_store_short v237, v94, s[4:5]
	s_add_u32 s4, s4, 0x800
	s_addc_u32 s5, s5, 0
	global_store_short v237, v95, s[4:5]
	s_add_u32 s4, s4, 0x800
	s_addc_u32 s5, s5, 0
	global_store_short v237, v96, s[4:5]
	s_add_u32 s4, s4, 0x800
	s_addc_u32 s5, s5, 0
	global_store_short v237, v97, s[4:5]
	s_add_u32 s4, s4, 0x800
	s_addc_u32 s5, s5, 0
	global_store_short v237, v98, s[4:5]
	s_add_u32 s4, s4, 0x800
	s_addc_u32 s5, s5, 0
	global_store_short v237, v99, s[4:5]
	s_add_u32 s4, s4, 0x800
	s_addc_u32 s5, s5, 0
	global_store_short v237, v100, s[4:5]
	s_add_u32 s4, s4, 0x800
	s_addc_u32 s5, s5, 0
	global_store_short v237, v101, s[4:5]
	s_add_u32 s4, s4, 0x800
	s_addc_u32 s5, s5, 0
	global_store_short v237, v102, s[4:5]
	s_add_u32 s4, s4, 0x800
	s_addc_u32 s5, s5, 0
	global_store_short v237, v103, s[4:5]
	s_add_u32 s4, s4, 0x800
	s_addc_u32 s5, s5, 0
	global_store_short v237, v104, s[4:5]
	s_add_u32 s4, s4, 0x800
	s_addc_u32 s5, s5, 0
	global_store_short v237, v105, s[4:5]
	s_add_u32 s4, s4, 0x800
	s_addc_u32 s5, s5, 0
	global_store_short v237, v106, s[4:5]
	s_add_u32 s4, s4, 0x800
	s_addc_u32 s5, s5, 0
	global_store_short v237, v107, s[4:5]
	s_add_u32 s4, s4, 0x800
	s_addc_u32 s5, s5, 0
	global_store_short v237, v108, s[4:5]
	s_add_u32 s4, s4, 0x800
	s_addc_u32 s5, s5, 0
	global_store_short v237, v109, s[4:5]
	s_add_u32 s4, s4, 0x800
	s_addc_u32 s5, s5, 0
	global_store_short v237, v110, s[4:5]
	s_add_u32 s4, s4, 0x800
	s_addc_u32 s5, s5, 0
	global_store_short v237, v111, s[4:5]
	s_add_u32 s4, s4, 0x800
	s_addc_u32 s5, s5, 0
	global_store_short v237, v112, s[4:5]
	s_add_u32 s4, s4, 0x800
	s_addc_u32 s5, s5, 0
	global_store_short v237, v113, s[4:5]
	s_add_u32 s4, s4, 0x800
	s_addc_u32 s5, s5, 0
	global_store_short v237, v114, s[4:5]
	s_add_u32 s4, s4, 0x800
	s_addc_u32 s5, s5, 0
	global_store_short v237, v115, s[4:5]
	s_add_u32 s4, s4, 0x800
	s_addc_u32 s5, s5, 0
	global_store_short v237, v116, s[4:5]
	s_add_u32 s4, s4, 0x800
	s_addc_u32 s5, s5, 0
	global_store_short v237, v117, s[4:5]
	s_add_u32 s4, s4, 0x800
	s_addc_u32 s5, s5, 0
	global_store_short v237, v118, s[4:5]
	s_add_u32 s4, s4, 0x800
	s_addc_u32 s5, s5, 0
	global_store_short v237, v119, s[4:5]
	s_add_u32 s4, s4, 0x800
	s_addc_u32 s5, s5, 0
	global_store_short v237, v120, s[4:5]
	s_add_u32 s4, s4, 0x800
	s_addc_u32 s5, s5, 0
	global_store_short v237, v121, s[4:5]
	s_add_u32 s69, s69, 1
	s_cmp_lt_u32 s69, s70
	s_cbranch_scc1 .Lmy_lrub_tile
	s_waitcnt lgkmcnt(0)
	s_barrier
	s_branch .LBB0_680
